# gMLP unit: parallel cache warm-up of VG/U tiles and spatial weights before the dependent load chain; attention K/V staging loads issued together
# baseline (speedup 1.0000x reference)
.LBB0_421:
	s_cmpk_gt_i32 s29, 0xff
	s_mov_b64 s[4:5], -1
	s_cbranch_scc0 .LBB0_423
	s_lshl_b32 s4, s29, 4
	v_mov_b32_e32 v3, v183
	s_and_b32 s8, s4, 0x7fffff80
	s_addk_i32 s8, 0xf000
	v_ashrrev_i32_e32 v28, 4, v3
	v_add_u32_e32 v0, s8, v28
	v_ashrrev_i32_e32 v1, 31, v0
	v_readlane_b32 s4, v254, 40
	v_readlane_b32 s5, v254, 41
	s_and_b32 s9, s29, 7
	v_lshlrev_b64 v[120:121], 11, v[0:1]
	v_and_b32_e32 v122, 15, v3
	v_lshlrev_b32_e32 v122, 4, v122
	v_lshl_add_u32 v122, s9, 8, v122
	v_mov_b32_e32 v123, 0
	v_lshl_add_u64 v[120:121], v[120:121], 0, v[122:123]
	v_lshl_add_u64 v[124:125], s[72:73], 0, v[120:121]
	v_lshl_add_u64 v[126:127], s[54:55], 0, v[120:121]
	v_mov_b32_e32 v122, 0x10000
	global_load_dwordx4 v[116:119], v[124:125], off
	global_load_dwordx4 v[116:119], v[126:127], off
	v_lshl_add_u64 v[124:125], v[124:125], 0, v[122:123]
	v_lshl_add_u64 v[126:127], v[126:127], 0, v[122:123]
	global_load_dwordx4 v[116:119], v[124:125], off
	global_load_dwordx4 v[116:119], v[126:127], off
	v_lshl_add_u64 v[124:125], v[124:125], 0, v[122:123]
	v_lshl_add_u64 v[126:127], v[126:127], 0, v[122:123]
	global_load_dwordx4 v[116:119], v[124:125], off
	global_load_dwordx4 v[116:119], v[126:127], off
	v_lshl_add_u64 v[124:125], v[124:125], 0, v[122:123]
	v_lshl_add_u64 v[126:127], v[126:127], 0, v[122:123]
	global_load_dwordx4 v[116:119], v[124:125], off
	global_load_dwordx4 v[116:119], v[126:127], off
	v_lshlrev_b32_e32 v120, 4, v3
	v_lshl_add_u32 v120, s9, 16, v120
	v_mov_b32_e32 v121, 0
	v_lshl_add_u64 v[120:121], s[4:5], 0, v[120:121]
	v_mov_b32_e32 v122, 0x2000
	global_load_dwordx4 v[116:119], v[120:121], off
	v_lshl_add_u64 v[120:121], v[120:121], 0, v[122:123]
	global_load_dwordx4 v[116:119], v[120:121], off
	v_lshl_add_u64 v[120:121], v[120:121], 0, v[122:123]
	global_load_dwordx4 v[116:119], v[120:121], off
	v_lshl_add_u64 v[120:121], v[120:121], 0, v[122:123]
	global_load_dwordx4 v[116:119], v[120:121], off
	v_lshl_add_u64 v[120:121], v[120:121], 0, v[122:123]
	global_load_dwordx4 v[116:119], v[120:121], off
	v_lshl_add_u64 v[120:121], v[120:121], 0, v[122:123]
	global_load_dwordx4 v[116:119], v[120:121], off
	v_lshl_add_u64 v[120:121], v[120:121], 0, v[122:123]
	global_load_dwordx4 v[116:119], v[120:121], off
	v_lshl_add_u64 v[120:121], v[120:121], 0, v[122:123]
	global_load_dwordx4 v[116:119], v[120:121], off
	v_lshlrev_b64 v[4:5], 6, v[0:1]
	v_lshl_add_u64 v[4:5], s[0:1], 0, v[4:5]
	global_load_dwordx4 v[6:9], v[4:5], off offset:32
	global_load_dwordx4 v[10:13], v[4:5], off offset:16
	global_load_dwordx4 v[14:17], v[4:5], off offset:48
	global_load_dwordx4 v[22:25], v[4:5], off
	s_and_b32 s6, s29, 7
	v_lshlrev_b64 v[0:1], 11, v[0:1]
	s_lshl_b32 s76, s6, 8
	v_and_b32_e32 v4, 15, v3
	v_lshl_add_u64 v[0:1], s[72:73], 0, v[0:1]
	v_lshlrev_b32_e32 v20, 4, v4
	v_lshl_add_u64 v[0:1], v[0:1], 0, s[76:77]
	v_readlane_b32 s36, v254, 30
	v_lshl_add_u64 v[0:1], v[0:1], 0, v[20:21]
	s_lshl_b32 s9, s6, 7
	s_lshl_b32 s4, s6, 9
	v_readlane_b32 s44, v254, 38
	global_load_dwordx4 v[34:37], v[0:1], off
	v_readlane_b32 s45, v254, 39
	s_add_u32 s4, s44, s4
	v_lshlrev_b32_e32 v0, 5, v4
	s_addc_u32 s5, s45, 0
	global_load_dwordx4 v[38:41], v0, s[4:5]
	global_load_dwordx4 v[42:45], v0, s[4:5] offset:16
	v_readlane_b32 s46, v254, 40
	s_lshl_b32 s6, s6, 16
	v_readlane_b32 s47, v254, 41
	v_lshlrev_b32_e32 v18, 7, v28
	s_add_u32 s6, s46, s6
	v_ashrrev_i32_e32 v19, 31, v18
	s_addc_u32 s7, s47, 0
	v_mov_b32_e32 v1, v21
	v_lshl_add_u64 v[18:19], v[18:19], 2, s[6:7]
	v_lshl_add_u64 v[18:19], v[18:19], 0, v[0:1]
	s_movk_i32 s10, 0x880
	v_readlane_b32 s48, v254, 42
	v_readlane_b32 s49, v254, 43
	v_readlane_b32 s37, v254, 31
	v_readlane_b32 s38, v254, 32
	v_readlane_b32 s39, v254, 33
	v_readlane_b32 s40, v254, 34
	v_readlane_b32 s41, v254, 35
	v_readlane_b32 s42, v254, 36
	v_readlane_b32 s43, v254, 37
	v_readlane_b32 s50, v254, 44
	v_readlane_b32 s51, v254, 45
	s_waitcnt vmcnt(0)
	v_mov_b32_e32 v27, v6
	v_mov_b32_e32 v47, v8
	v_mov_b32_e32 v48, v10
	v_mov_b32_e32 v49, v14
	v_mov_b32_e32 v14, v11
	v_mov_b32_e32 v10, v12
	v_mov_b32_e32 v11, v16
	v_mov_b32_e32 v16, v13
	v_mov_b32_e32 v26, v22
	v_mov_b32_e32 v6, v23
	v_mov_b32_e32 v46, v24
	v_mov_b32_e32 v8, v25
	v_pk_add_f32 v[12:13], v[48:49], v[14:15]
	v_pk_add_f32 v[10:11], v[10:11], v[16:17]
	v_pk_add_f32 v[6:7], v[26:27], v[6:7]
	v_pk_add_f32 v[8:9], v[46:47], v[8:9]
	v_pk_add_f32 v[10:11], v[12:13], v[10:11]
	v_pk_add_f32 v[6:7], v[6:7], v[8:9]
	v_lshlrev_b32_e32 v12, 16, v34
	v_pk_add_f32 v[6:7], v[6:7], v[10:11]
	v_and_b32_e32 v13, 0xffff0000, v34
	v_add_f32_e32 v2, v6, v7
	v_fmamk_f32 v2, v2, 0x3a800000, v29
	v_mul_f32_e32 v5, 0x4b800000, v2
	v_cmp_gt_f32_e32 vcc, s21, v2
	v_lshlrev_b32_e32 v16, 16, v36
	v_and_b32_e32 v17, 0xffff0000, v36
	v_cndmask_b32_e32 v2, v2, v5, vcc
	v_rsq_f32_e32 v2, v2
	v_lshlrev_b32_e32 v14, 16, v35
	v_and_b32_e32 v15, 0xffff0000, v35
	v_lshlrev_b32_e32 v6, 16, v37
	v_mul_f32_e32 v5, 0x45800000, v2
	v_cndmask_b32_e32 v2, v2, v5, vcc
	v_and_b32_e32 v7, 0xffff0000, v37
	v_pk_mul_f32 v[8:9], v[2:3], v[12:13] op_sel_hi:[0,1]
	v_pk_mul_f32 v[12:13], v[2:3], v[16:17] op_sel_hi:[0,1]
	v_pk_mul_f32 v[10:11], v[2:3], v[14:15] op_sel_hi:[0,1]
	v_pk_mul_f32 v[6:7], v[2:3], v[6:7] op_sel_hi:[0,1]
	v_pk_mul_f32 v[12:13], v[42:43], v[12:13]
	v_pk_mul_f32 v[10:11], v[40:41], v[10:11]
	v_pk_mul_f32 v[8:9], v[38:39], v[8:9]
	v_pk_mul_f32 v[6:7], v[44:45], v[6:7]
	s_nop 1
	v_cvt_pk_bf16_f32 v36, v8, v9
	s_nop 1
	v_cvt_pk_bf16_f32 v37, v10, v11
	s_nop 1
	v_cvt_pk_bf16_f32 v13, v12, v13
	v_mad_u32_u24 v12, v4, s10, 16
	s_nop 1
	v_cvt_pk_bf16_f32 v38, v6, v7
	global_load_dwordx4 v[14:17], v[18:19], off
	global_load_dwordx4 v[22:25], v[18:19], off offset:16
	v_lshlrev_b32_e32 v7, 3, v4
	v_mov_b32_e32 v2, s77
	v_lshl_add_u32 v19, v28, 1, v12
	v_or_b32_e32 v11, 4, v7
	v_cmp_gt_i32_e32 vcc, v7, v28
	v_mov_b32_e32 v18, s77
	ds_write_b16 v19, v36
	ds_write_b16_d16_hi v19, v36 offset:272
	ds_write_b16 v19, v37 offset:544
	ds_write_b16_d16_hi v19, v37 offset:816
	ds_write_b16 v19, v13 offset:1088
	ds_write_b16_d16_hi v19, v13 offset:1360
	ds_write_b16 v19, v38 offset:1632
	ds_write_b16_d16_hi v19, v38 offset:1904
	v_or_b32_e32 v8, 5, v7
	v_add_u32_e32 v5, 0x200, v3
	v_or_b32_e32 v9, 6, v7
	v_ashrrev_i32_e32 v58, 4, v5
	v_or_b32_e32 v10, 7, v7
	v_or_b32_e32 v5, 2, v7
	v_add_u32_e32 v26, s8, v58
	v_or_b32_e32 v6, 3, v7
	v_ashrrev_i32_e32 v27, 31, v26
	v_lshlrev_b64 v[34:35], 6, v[26:27]
	v_lshl_add_u64 v[42:43], s[0:1], 0, v[34:35]
	s_movk_i32 s10, 0xf790
	s_waitcnt vmcnt(1)
	v_cndmask_b32_e32 v13, v16, v16, vcc
	v_cndmask_b32_e32 v19, v17, v17, vcc
	v_cndmask_b32_e32 v2, v14, v2, vcc
	v_cmp_gt_i32_e32 vcc, v11, v28
	s_waitcnt vmcnt(0)
	s_nop 0
	v_cndmask_b32_e32 v18, v22, v18, vcc
	v_cndmask_b32_e32 v22, v25, v25, vcc
	v_cndmask_b32_e32 v24, v24, v24, vcc
	v_cndmask_b32_e32 v23, v23, v23, vcc
	v_cmp_lt_i32_e32 vcc, v7, v28
	s_nop 1
	v_cndmask_b32_e32 v2, v2, v14, vcc
	v_cndmask_b32_e32 v14, v19, v17, vcc
	v_cndmask_b32_e32 v13, v13, v16, vcc
	v_cndmask_b32_e32 v15, 0, v15, vcc
	v_cmp_le_i32_e32 vcc, v8, v28
	s_nop 1
	v_cndmask_b32_e32 v16, 0, v23, vcc
	v_cmp_le_i32_e32 vcc, v9, v28
	s_nop 1
	v_cndmask_b32_e32 v17, 0, v24, vcc
	v_cmp_le_i32_e32 vcc, v10, v28
	s_nop 1
	v_cndmask_b32_e32 v19, 0, v22, vcc
	v_cmp_le_i32_e32 vcc, v5, v28
	s_nop 1
	v_cndmask_b32_e32 v13, 0, v13, vcc
	v_cmp_le_i32_e32 vcc, v6, v28
	s_nop 1
	v_cndmask_b32_e32 v22, 0, v14, vcc
	s_nop 1
	v_cvt_pk_bf16_f32 v14, v2, v15
	s_nop 1
	v_cvt_pk_bf16_f32 v15, v13, v22
	s_nop 1
	v_cvt_pk_bf16_f32 v16, v18, v16
	s_nop 1
	v_cvt_pk_bf16_f32 v17, v17, v19
	global_load_dwordx4 v[22:25], v[42:43], off
	global_load_dwordx4 v[34:37], v[42:43], off offset:32
	global_load_dwordx4 v[38:41], v[42:43], off offset:16
	s_nop 0
	global_load_dwordx4 v[42:45], v[42:43], off offset:48
	v_lshlrev_b64 v[18:19], 11, v[26:27]
	v_lshl_add_u64 v[18:19], s[72:73], 0, v[18:19]
	v_lshl_add_u64 v[18:19], v[18:19], 0, s[76:77]
	v_lshl_add_u64 v[18:19], v[18:19], 0, v[20:21]
	global_load_dwordx4 v[46:49], v[18:19], off
	global_load_dwordx4 v[50:53], v0, s[4:5]
	global_load_dwordx4 v[54:57], v0, s[4:5] offset:16
	v_mad_i32_i24 v2, v4, s10, v12
	v_mad_u64_u32 v[26:27], s[10:11], v28, s24, v[2:3]
	ds_write_b128 v26, v[14:17] offset:34816
	v_lshlrev_b32_e32 v18, 7, v58
	v_ashrrev_i32_e32 v19, 31, v18
	v_lshl_add_u64 v[18:19], v[18:19], 2, s[6:7]
	v_lshl_add_u64 v[18:19], v[18:19], 0, v[0:1]
	s_waitcnt vmcnt(6)
	v_mov_b32_e32 v14, v22
	s_waitcnt vmcnt(5)
	v_mov_b32_e32 v15, v34
	v_mov_b32_e32 v34, v23
	v_mov_b32_e32 v16, v24
	v_mov_b32_e32 v17, v36
	v_mov_b32_e32 v36, v25
	s_waitcnt vmcnt(4)
	v_mov_b32_e32 v22, v38
	s_waitcnt vmcnt(3)
	v_mov_b32_e32 v23, v42
	v_mov_b32_e32 v42, v39
	v_mov_b32_e32 v24, v40
	v_mov_b32_e32 v25, v44
	v_mov_b32_e32 v44, v41
	v_pk_add_f32 v[14:15], v[14:15], v[34:35]
	v_pk_add_f32 v[16:17], v[16:17], v[36:37]
	v_pk_add_f32 v[22:23], v[22:23], v[42:43]
	v_pk_add_f32 v[24:25], v[24:25], v[44:45]
	v_pk_add_f32 v[14:15], v[14:15], v[16:17]
	v_pk_add_f32 v[16:17], v[22:23], v[24:25]
	s_waitcnt vmcnt(2)
	v_lshlrev_b32_e32 v26, 16, v46
	v_pk_add_f32 v[14:15], v[14:15], v[16:17]
	v_and_b32_e32 v27, 0xffff0000, v46
	v_add_f32_e32 v13, v14, v15
	v_fmamk_f32 v13, v13, 0x3a800000, v29
	v_mul_f32_e32 v14, 0x4b800000, v13
	v_cmp_gt_f32_e32 vcc, s21, v13
	v_lshlrev_b32_e32 v38, 16, v47
	v_and_b32_e32 v39, 0xffff0000, v47
	v_cndmask_b32_e32 v13, v13, v14, vcc
	v_rsq_f32_e32 v13, v13
	v_lshlrev_b32_e32 v40, 16, v48
	v_and_b32_e32 v41, 0xffff0000, v48
	v_lshlrev_b32_e32 v14, 16, v49
	v_mul_f32_e32 v16, 0x45800000, v13
	v_and_b32_e32 v15, 0xffff0000, v49
	v_cndmask_b32_e32 v16, v13, v16, vcc
	v_pk_mul_f32 v[22:23], v[16:17], v[26:27] op_sel_hi:[0,1]
	v_pk_mul_f32 v[24:25], v[16:17], v[38:39] op_sel_hi:[0,1]
	v_pk_mul_f32 v[26:27], v[16:17], v[40:41] op_sel_hi:[0,1]
	v_pk_mul_f32 v[14:15], v[16:17], v[14:15] op_sel_hi:[0,1]
	s_waitcnt vmcnt(1)
	v_pk_mul_f32 v[16:17], v[52:53], v[24:25]
	v_pk_mul_f32 v[22:23], v[50:51], v[22:23]
	s_waitcnt vmcnt(0)
	v_pk_mul_f32 v[14:15], v[56:57], v[14:15]
	v_pk_mul_f32 v[24:25], v[54:55], v[26:27]
	s_nop 1
	v_cvt_pk_bf16_f32 v13, v22, v23
	s_nop 1
	v_cvt_pk_bf16_f32 v27, v16, v17
	v_cmp_gt_i32_e32 vcc, v7, v58
	s_nop 1
	v_cvt_pk_bf16_f32 v28, v24, v25
	s_nop 1
	v_cvt_pk_bf16_f32 v36, v14, v15
	global_load_dwordx4 v[14:17], v[18:19], off
	global_load_dwordx4 v[22:25], v[18:19], off offset:16
	v_add_u32_e32 v19, 0x400, v3
	v_mov_b32_e32 v18, s77
	v_ashrrev_i32_e32 v59, 4, v19
	v_lshl_add_u32 v19, v58, 1, v12
	v_mov_b32_e32 v26, s77
	ds_write_b16 v19, v13
	ds_write_b16_d16_hi v19, v13 offset:272
	ds_write_b16 v19, v27 offset:544
	ds_write_b16_d16_hi v19, v27 offset:816
	ds_write_b16 v19, v28 offset:1088
	ds_write_b16_d16_hi v19, v28 offset:1360
	ds_write_b16 v19, v36 offset:1632
	ds_write_b16_d16_hi v19, v36 offset:1904
	v_add_u32_e32 v46, s8, v59
	v_ashrrev_i32_e32 v47, 31, v46
	v_lshlrev_b64 v[34:35], 6, v[46:47]
	v_lshl_add_u64 v[42:43], s[0:1], 0, v[34:35]
	s_waitcnt vmcnt(1)
	v_cndmask_b32_e32 v13, v16, v16, vcc
	v_cndmask_b32_e32 v19, v17, v17, vcc
	v_cndmask_b32_e32 v18, v14, v18, vcc
	v_cmp_gt_i32_e32 vcc, v11, v58
	s_waitcnt vmcnt(0)
	s_nop 0
	v_cndmask_b32_e32 v22, v22, v26, vcc
	v_cndmask_b32_e32 v25, v25, v25, vcc
	v_cndmask_b32_e32 v24, v24, v24, vcc
	v_cndmask_b32_e32 v23, v23, v23, vcc
	v_cmp_lt_i32_e32 vcc, v7, v58
	v_mad_u64_u32 v[26:27], s[10:11], v58, s24, v[2:3]
	s_nop 0
	v_cndmask_b32_e32 v14, v18, v14, vcc
	v_cndmask_b32_e32 v17, v19, v17, vcc
	v_cndmask_b32_e32 v13, v13, v16, vcc
	v_cndmask_b32_e32 v15, 0, v15, vcc
	v_cmp_le_i32_e32 vcc, v8, v58
	s_nop 1
	v_cvt_pk_bf16_f32 v14, v14, v15
	s_nop 1
	v_cndmask_b32_e32 v16, 0, v23, vcc
	v_cmp_le_i32_e32 vcc, v9, v58
	s_nop 1
	v_cndmask_b32_e32 v18, 0, v24, vcc
	v_cmp_le_i32_e32 vcc, v10, v58
	s_nop 1
	v_cndmask_b32_e32 v19, 0, v25, vcc
	v_cmp_le_i32_e32 vcc, v5, v58
	s_nop 1
	v_cndmask_b32_e32 v13, 0, v13, vcc
	v_cmp_le_i32_e32 vcc, v6, v58
	s_nop 1
	v_cndmask_b32_e32 v17, 0, v17, vcc
	s_nop 1
	v_cvt_pk_bf16_f32 v15, v13, v17
	s_nop 1
	v_cvt_pk_bf16_f32 v16, v22, v16
	s_nop 1
	v_cvt_pk_bf16_f32 v17, v18, v19
	global_load_dwordx4 v[22:25], v[42:43], off
	global_load_dwordx4 v[34:37], v[42:43], off offset:32
	global_load_dwordx4 v[38:41], v[42:43], off offset:16
	s_nop 0
	global_load_dwordx4 v[42:45], v[42:43], off offset:48
	v_lshlrev_b64 v[18:19], 11, v[46:47]
	v_lshl_add_u64 v[18:19], s[72:73], 0, v[18:19]
	v_lshl_add_u64 v[18:19], v[18:19], 0, s[76:77]
	v_lshl_add_u64 v[18:19], v[18:19], 0, v[20:21]
	global_load_dwordx4 v[46:49], v[18:19], off
	global_load_dwordx4 v[50:53], v0, s[4:5]
	global_load_dwordx4 v[54:57], v0, s[4:5] offset:16
	ds_write_b128 v26, v[14:17] offset:34816
	v_lshlrev_b32_e32 v18, 7, v59
	v_ashrrev_i32_e32 v19, 31, v18
	v_lshl_add_u64 v[18:19], v[18:19], 2, s[6:7]
	v_lshl_add_u64 v[18:19], v[18:19], 0, v[0:1]
	s_waitcnt vmcnt(6)
	v_mov_b32_e32 v14, v22
	s_waitcnt vmcnt(5)
	v_mov_b32_e32 v15, v34
	v_mov_b32_e32 v34, v23
	v_mov_b32_e32 v16, v24
	v_mov_b32_e32 v17, v36
	v_mov_b32_e32 v36, v25
	s_waitcnt vmcnt(4)
	v_mov_b32_e32 v22, v38
	s_waitcnt vmcnt(3)
	v_mov_b32_e32 v23, v42
	v_mov_b32_e32 v42, v39
	v_mov_b32_e32 v24, v40
	v_mov_b32_e32 v25, v44
	v_mov_b32_e32 v44, v41
	v_pk_add_f32 v[14:15], v[14:15], v[34:35]
	v_pk_add_f32 v[16:17], v[16:17], v[36:37]
	v_pk_add_f32 v[22:23], v[22:23], v[42:43]
	v_pk_add_f32 v[24:25], v[24:25], v[44:45]
	v_pk_add_f32 v[14:15], v[14:15], v[16:17]
	v_pk_add_f32 v[16:17], v[22:23], v[24:25]
	s_waitcnt vmcnt(2)
	v_lshlrev_b32_e32 v26, 16, v46
	v_pk_add_f32 v[14:15], v[14:15], v[16:17]
	v_and_b32_e32 v27, 0xffff0000, v46
	v_add_f32_e32 v13, v14, v15
	v_fmamk_f32 v13, v13, 0x3a800000, v29
	v_mul_f32_e32 v14, 0x4b800000, v13
	v_cmp_gt_f32_e32 vcc, s21, v13
	v_lshlrev_b32_e32 v38, 16, v47
	v_and_b32_e32 v39, 0xffff0000, v47
	v_cndmask_b32_e32 v13, v13, v14, vcc
	v_rsq_f32_e32 v13, v13
	v_lshlrev_b32_e32 v40, 16, v48
	v_and_b32_e32 v41, 0xffff0000, v48
	v_lshlrev_b32_e32 v14, 16, v49
	v_mul_f32_e32 v16, 0x45800000, v13
	v_and_b32_e32 v15, 0xffff0000, v49
	v_cndmask_b32_e32 v16, v13, v16, vcc
	v_pk_mul_f32 v[22:23], v[16:17], v[26:27] op_sel_hi:[0,1]
	v_pk_mul_f32 v[24:25], v[16:17], v[38:39] op_sel_hi:[0,1]
	v_pk_mul_f32 v[26:27], v[16:17], v[40:41] op_sel_hi:[0,1]
	v_pk_mul_f32 v[14:15], v[16:17], v[14:15] op_sel_hi:[0,1]
	s_waitcnt vmcnt(1)
	v_pk_mul_f32 v[16:17], v[52:53], v[24:25]
	v_pk_mul_f32 v[22:23], v[50:51], v[22:23]
	s_waitcnt vmcnt(0)
	v_pk_mul_f32 v[14:15], v[56:57], v[14:15]
	v_pk_mul_f32 v[24:25], v[54:55], v[26:27]
	s_nop 1
	v_cvt_pk_bf16_f32 v13, v22, v23
	s_nop 1
	v_cvt_pk_bf16_f32 v27, v16, v17
	v_cmp_gt_i32_e32 vcc, v7, v59
	s_nop 1
	v_cvt_pk_bf16_f32 v28, v24, v25
	s_nop 1
	v_cvt_pk_bf16_f32 v36, v14, v15
	global_load_dwordx4 v[14:17], v[18:19], off
	global_load_dwordx4 v[22:25], v[18:19], off offset:16
	v_add_u32_e32 v19, 0x600, v3
	v_mov_b32_e32 v18, s77
	v_ashrrev_i32_e32 v58, 4, v19
	v_lshl_add_u32 v19, v59, 1, v12
	v_mov_b32_e32 v26, s77
	ds_write_b16 v19, v13
	ds_write_b16_d16_hi v19, v13 offset:272
	ds_write_b16 v19, v27 offset:544
	ds_write_b16_d16_hi v19, v27 offset:816
	ds_write_b16 v19, v28 offset:1088
	ds_write_b16_d16_hi v19, v28 offset:1360
	ds_write_b16 v19, v36 offset:1632
	ds_write_b16_d16_hi v19, v36 offset:1904
	v_add_u32_e32 v46, s8, v58
	v_ashrrev_i32_e32 v47, 31, v46
	v_lshlrev_b64 v[34:35], 6, v[46:47]
	v_lshl_add_u64 v[42:43], s[0:1], 0, v[34:35]
	s_waitcnt vmcnt(1)
	v_cndmask_b32_e32 v13, v16, v16, vcc
	v_cndmask_b32_e32 v19, v17, v17, vcc
	v_cndmask_b32_e32 v18, v14, v18, vcc
	v_cmp_gt_i32_e32 vcc, v11, v59
	s_waitcnt vmcnt(0)
	s_nop 0
	v_cndmask_b32_e32 v22, v22, v26, vcc
	v_cndmask_b32_e32 v25, v25, v25, vcc
	v_cndmask_b32_e32 v24, v24, v24, vcc
	v_cndmask_b32_e32 v23, v23, v23, vcc
	v_cmp_lt_i32_e32 vcc, v7, v59
	s_nop 1
	v_cndmask_b32_e32 v14, v18, v14, vcc
	v_cndmask_b32_e32 v17, v19, v17, vcc
	v_cndmask_b32_e32 v13, v13, v16, vcc
	v_cndmask_b32_e32 v15, 0, v15, vcc
	v_cmp_le_i32_e32 vcc, v8, v59
	s_nop 1
	v_cvt_pk_bf16_f32 v14, v14, v15
	s_nop 1
	v_cndmask_b32_e32 v16, 0, v23, vcc
	v_cmp_le_i32_e32 vcc, v9, v59
	s_nop 1
	v_cndmask_b32_e32 v18, 0, v24, vcc
	v_cmp_le_i32_e32 vcc, v10, v59
	s_nop 1
	v_cndmask_b32_e32 v19, 0, v25, vcc
	v_cmp_le_i32_e32 vcc, v5, v59
	s_nop 1
	v_cndmask_b32_e32 v13, 0, v13, vcc
	v_cmp_le_i32_e32 vcc, v6, v59
	s_nop 1
	v_cndmask_b32_e32 v17, 0, v17, vcc
	s_nop 1
	v_cvt_pk_bf16_f32 v15, v13, v17
	s_nop 1
	v_cvt_pk_bf16_f32 v16, v22, v16
	s_nop 1
	v_cvt_pk_bf16_f32 v17, v18, v19
	global_load_dwordx4 v[22:25], v[42:43], off
	global_load_dwordx4 v[34:37], v[42:43], off offset:32
	global_load_dwordx4 v[38:41], v[42:43], off offset:16
	s_nop 0
	global_load_dwordx4 v[42:45], v[42:43], off offset:48
	v_lshlrev_b64 v[18:19], 11, v[46:47]
	v_lshl_add_u64 v[18:19], s[72:73], 0, v[18:19]
	v_lshl_add_u64 v[18:19], v[18:19], 0, s[76:77]
	v_lshl_add_u64 v[18:19], v[18:19], 0, v[20:21]
	global_load_dwordx4 v[46:49], v[18:19], off
	global_load_dwordx4 v[50:53], v0, s[4:5]
	global_load_dwordx4 v[54:57], v0, s[4:5] offset:16
	v_lshlrev_b32_e32 v18, 7, v58
	v_ashrrev_i32_e32 v19, 31, v18
	v_mad_u64_u32 v[26:27], s[4:5], v59, s24, v[2:3]
	v_lshl_add_u64 v[18:19], v[18:19], 2, s[6:7]
	v_lshl_add_u64 v[0:1], v[18:19], 0, v[0:1]
	ds_write_b128 v26, v[14:17] offset:34816
	s_waitcnt vmcnt(6)
	v_mov_b32_e32 v14, v22
	s_waitcnt vmcnt(5)
	v_mov_b32_e32 v15, v34
	v_mov_b32_e32 v34, v23
	v_mov_b32_e32 v16, v24
	v_mov_b32_e32 v17, v36
	v_mov_b32_e32 v36, v25
	s_waitcnt vmcnt(4)
	v_mov_b32_e32 v18, v38
	s_waitcnt vmcnt(3)
	v_mov_b32_e32 v19, v42
	v_mov_b32_e32 v42, v39
	v_mov_b32_e32 v22, v40
	v_mov_b32_e32 v23, v44
	v_mov_b32_e32 v44, v41
	v_pk_add_f32 v[14:15], v[14:15], v[34:35]
	v_pk_add_f32 v[16:17], v[16:17], v[36:37]
	v_pk_add_f32 v[18:19], v[18:19], v[42:43]
	v_pk_add_f32 v[22:23], v[22:23], v[44:45]
	v_pk_add_f32 v[14:15], v[14:15], v[16:17]
	v_pk_add_f32 v[16:17], v[18:19], v[22:23]
	s_waitcnt vmcnt(2)
	v_lshlrev_b32_e32 v24, 16, v46
	v_pk_add_f32 v[14:15], v[14:15], v[16:17]
	v_and_b32_e32 v25, 0xffff0000, v46
	v_add_f32_e32 v13, v14, v15
	v_fmamk_f32 v13, v13, 0x3a800000, v29
	v_mul_f32_e32 v14, 0x4b800000, v13
	v_cmp_gt_f32_e32 vcc, s21, v13
	v_lshlrev_b32_e32 v26, 16, v47
	v_and_b32_e32 v27, 0xffff0000, v47
	v_cndmask_b32_e32 v13, v13, v14, vcc
	v_rsq_f32_e32 v13, v13
	v_lshlrev_b32_e32 v38, 16, v48
	v_and_b32_e32 v39, 0xffff0000, v48
	v_lshlrev_b32_e32 v14, 16, v49
	v_mul_f32_e32 v16, 0x45800000, v13
	v_and_b32_e32 v15, 0xffff0000, v49
	v_cndmask_b32_e32 v16, v13, v16, vcc
	v_pk_mul_f32 v[18:19], v[16:17], v[24:25] op_sel_hi:[0,1]
	v_pk_mul_f32 v[22:23], v[16:17], v[26:27] op_sel_hi:[0,1]
	v_pk_mul_f32 v[24:25], v[16:17], v[38:39] op_sel_hi:[0,1]
	v_pk_mul_f32 v[14:15], v[16:17], v[14:15] op_sel_hi:[0,1]
	s_waitcnt vmcnt(1)
	v_pk_mul_f32 v[16:17], v[52:53], v[22:23]
	s_waitcnt vmcnt(0)
	v_pk_mul_f32 v[14:15], v[56:57], v[14:15]
	v_pk_mul_f32 v[22:23], v[54:55], v[24:25]
	v_pk_mul_f32 v[18:19], v[50:51], v[18:19]
	v_ashrrev_i32_e32 v41, 2, v3
	s_nop 1
	v_cvt_pk_bf16_f32 v28, v18, v19
	s_nop 1
	v_cvt_pk_bf16_f32 v38, v16, v17
	s_nop 1
	v_cvt_pk_bf16_f32 v39, v22, v23
	s_nop 1
	v_cvt_pk_bf16_f32 v15, v14, v15
	global_load_dwordx4 v[22:25], v[0:1], off
	global_load_dwordx4 v[34:37], v[0:1], off offset:16
	v_mov_b32_e32 v0, s77
	v_bfe_u32 v40, v3, 4, 2
	v_and_b32_e32 v1, -16, v41
	v_or_b32_e32 v13, s9, v4
	v_cmp_gt_i32_e32 vcc, v7, v58
	v_mov_b32_e32 v14, s77
	v_lshl_add_u32 v42, v58, 1, v12
	v_ashrrev_i32_e32 v17, 31, v1
	v_lshl_or_b32 v16, v40, 2, v1
	v_lshlrev_b32_e32 v46, 2, v13
	v_mad_u64_u32 v[12:13], s[4:5], v58, s24, v[2:3]
	ds_write_b16 v42, v28
	ds_write_b16_d16_hi v42, v28 offset:272
	ds_write_b16 v42, v38 offset:544
	ds_write_b16_d16_hi v42, v38 offset:816
	ds_write_b16 v42, v39 offset:1088
	ds_write_b16_d16_hi v42, v39 offset:1360
	ds_write_b16 v42, v15 offset:1632
	ds_write_b16_d16_hi v42, v15 offset:1904
	v_or_b32_e32 v18, s8, v4
	v_lshl_or_b32 v20, v18, 10, s9
	v_lshl_add_u64 v[18:19], v[16:17], 0, v[20:21]
	v_lshlrev_b64 v[18:19], 1, v[18:19]
	v_lshl_add_u64 v[26:27], s[54:55], 0, v[18:19]
	v_lshl_add_u64 v[18:19], s[74:75], 0, v[18:19]
	v_mov_b32_e32 v43, v21
	v_or_b32_e32 v42, 0x14000, v20
	s_waitcnt vmcnt(1)
	v_cndmask_b32_e32 v1, v24, v24, vcc
	v_cndmask_b32_e32 v2, v25, v25, vcc
	v_cndmask_b32_e32 v0, v22, v0, vcc
	v_cmp_gt_i32_e32 vcc, v11, v58
	s_waitcnt vmcnt(0)
	s_nop 0
	v_cndmask_b32_e32 v11, v34, v14, vcc
	v_cndmask_b32_e32 v13, v37, v37, vcc
	v_cndmask_b32_e32 v14, v36, v36, vcc
	v_cndmask_b32_e32 v15, v35, v35, vcc
	v_cmp_lt_i32_e32 vcc, v7, v58
	s_nop 1
	v_cndmask_b32_e32 v0, v0, v22, vcc
	v_cndmask_b32_e32 v2, v2, v25, vcc
	v_cndmask_b32_e32 v1, v1, v24, vcc
	v_cndmask_b32_e32 v7, 0, v23, vcc
	v_cmp_le_i32_e32 vcc, v8, v58
	s_nop 1
	v_cndmask_b32_e32 v8, 0, v15, vcc
	v_cmp_le_i32_e32 vcc, v9, v58
	s_nop 1
	v_cndmask_b32_e32 v9, 0, v14, vcc
	v_cmp_le_i32_e32 vcc, v10, v58
	s_nop 1
	v_cndmask_b32_e32 v10, 0, v13, vcc
	v_cmp_le_i32_e32 vcc, v5, v58
	s_nop 1
	v_cndmask_b32_e32 v1, 0, v1, vcc
	v_cmp_le_i32_e32 vcc, v6, v58
	s_nop 1
	v_cvt_pk_bf16_f32 v6, v0, v7
	v_lshl_add_u32 v0, v40, 4, 16
	v_mad_u32_u24 v47, v4, s24, v0
	v_cndmask_b32_e32 v2, 0, v2, vcc
	s_nop 1
	v_cvt_pk_bf16_f32 v7, v1, v2
	s_nop 1
	v_cvt_pk_bf16_f32 v8, v11, v8
	s_nop 1
	v_cvt_pk_bf16_f32 v9, v9, v10
	ds_write_b128 v12, v[6:9] offset:34816
	s_waitcnt lgkmcnt(0)
	s_barrier
	global_load_dwordx2 v[26:27], v[26:27], off
	s_nop 0
	global_load_dword v28, v46, s[48:49]
	v_mov_b32_e32 v1, v21
	v_bfi_b32 v2, -16, v41, v3
	v_mad_u64_u32 v[2:3], s[4:5], v2, s24, v[0:1]
	ds_read_b128 v[4:7], v2
	ds_read_b128 v[22:25], v47 offset:34816
	s_waitcnt lgkmcnt(0)
	v_mfma_f32_16x16x32_bf16 v[22:25], v[4:7], v[22:25], 0
	v_or_b32_e32 v0, 0x4000, v20
	v_lshl_add_u64 v[0:1], v[16:17], 0, v[0:1]
	v_lshlrev_b64 v[34:35], 1, v[0:1]
	v_lshl_add_u64 v[36:37], s[54:55], 0, v[34:35]
	ds_read_b128 v[12:15], v2 offset:64
	ds_read_b128 v[8:11], v2 offset:128
	ds_read_b128 v[0:3], v2 offset:192
	v_lshl_add_u64 v[34:35], s[74:75], 0, v[34:35]
	s_mov_b64 s[4:5], 0
	s_waitcnt vmcnt(1)
	v_lshlrev_b32_e32 v38, 16, v26
	s_waitcnt vmcnt(0)
	v_add_f32_e32 v22, v22, v28
	v_and_b32_e32 v26, 0xffff0000, v26
	v_add_f32_e32 v23, v23, v28
	v_lshlrev_b32_e32 v39, 16, v27
	v_add_f32_e32 v24, v24, v28
	v_and_b32_e32 v27, 0xffff0000, v27
	v_add_f32_e32 v25, v25, v28
	v_mul_f32_e32 v22, v22, v38
	v_mul_f32_e32 v23, v23, v26
	v_mul_f32_e32 v24, v24, v39
	v_mul_f32_e32 v25, v25, v27
	s_nop 1
	v_cvt_pk_bf16_f32 v22, v22, v23
	s_nop 1
	v_cvt_pk_bf16_f32 v23, v24, v25
	global_store_dwordx2 v[18:19], v[22:23], off
	global_load_dwordx2 v[18:19], v[36:37], off
	s_nop 0
	global_load_dword v28, v46, s[48:49] offset:64
	ds_read_b128 v[22:25], v47 offset:39168
	s_waitcnt lgkmcnt(0)
	v_mfma_f32_16x16x32_bf16 v[22:25], v[4:7], v[22:25], 0
	v_mov_b32_e32 v27, v21
	v_or_b32_e32 v26, 0x8000, v20
	v_lshl_add_u64 v[26:27], v[16:17], 0, v[26:27]
	v_lshlrev_b64 v[26:27], 1, v[26:27]
	v_lshl_add_u64 v[36:37], s[54:55], 0, v[26:27]
	v_lshl_add_u64 v[26:27], s[74:75], 0, v[26:27]
	s_waitcnt vmcnt(1)
	v_lshlrev_b32_e32 v38, 16, v18
	v_and_b32_e32 v18, 0xffff0000, v18
	s_waitcnt vmcnt(0)
	v_add_f32_e32 v23, v23, v28
	v_lshlrev_b32_e32 v39, 16, v19
	v_and_b32_e32 v19, 0xffff0000, v19
	v_add_f32_e32 v25, v25, v28
	v_add_f32_e32 v22, v22, v28
	v_add_f32_e32 v24, v24, v28
	v_mul_f32_e32 v18, v23, v18
	v_mul_f32_e32 v19, v25, v19
	v_mul_f32_e32 v22, v22, v38
	v_mul_f32_e32 v23, v24, v39
	s_nop 1
	v_cvt_pk_bf16_f32 v18, v22, v18
	s_nop 1
	v_cvt_pk_bf16_f32 v19, v23, v19
	global_store_dwordx2 v[34:35], v[18:19], off
	global_load_dwordx2 v[18:19], v[36:37], off
	s_nop 0
	global_load_dword v28, v46, s[48:49] offset:128
	ds_read_b128 v[22:25], v47 offset:43520
	v_mov_b32_e32 v35, v21
	v_or_b32_e32 v34, 0xc000, v20
	v_lshl_add_u64 v[38:39], v[16:17], 0, v[34:35]
	ds_read_b128 v[34:37], v47 offset:43584
	s_waitcnt lgkmcnt(1)
	v_mfma_f32_16x16x32_bf16 v[22:25], v[4:7], v[22:25], 0
	v_lshlrev_b64 v[38:39], 1, v[38:39]
	v_lshl_add_u64 v[40:41], s[54:55], 0, v[38:39]
	v_lshl_add_u64 v[38:39], s[74:75], 0, v[38:39]
	s_waitcnt lgkmcnt(0)
	v_mfma_f32_16x16x32_bf16 v[22:25], v[12:15], v[34:37], v[22:25]
	s_waitcnt vmcnt(1)
	v_lshlrev_b32_e32 v34, 16, v18
	v_and_b32_e32 v18, 0xffff0000, v18
	s_waitcnt vmcnt(0)
	s_nop 3
	v_add_f32_e32 v23, v23, v28
	v_lshlrev_b32_e32 v35, 16, v19
	v_and_b32_e32 v19, 0xffff0000, v19
	v_add_f32_e32 v25, v25, v28
	v_add_f32_e32 v22, v22, v28
	v_add_f32_e32 v24, v24, v28
	v_mul_f32_e32 v18, v23, v18
	v_mul_f32_e32 v19, v25, v19
	v_mul_f32_e32 v22, v22, v34
	v_mul_f32_e32 v23, v24, v35
	s_nop 1
	v_cvt_pk_bf16_f32 v18, v22, v18
	s_nop 1
	v_cvt_pk_bf16_f32 v19, v23, v19
	global_store_dwordx2 v[26:27], v[18:19], off
	global_load_dwordx2 v[18:19], v[40:41], off
	s_nop 0
	global_load_dword v28, v46, s[48:49] offset:192
	ds_read_b128 v[22:25], v47 offset:47872
	ds_read_b128 v[34:37], v47 offset:47936
	s_waitcnt lgkmcnt(1)
	v_mfma_f32_16x16x32_bf16 v[22:25], v[4:7], v[22:25], 0
	v_mov_b32_e32 v27, v21
	v_or_b32_e32 v26, 0x10000, v20
	v_lshl_add_u64 v[26:27], v[16:17], 0, v[26:27]
	s_waitcnt lgkmcnt(0)
	v_mfma_f32_16x16x32_bf16 v[22:25], v[12:15], v[34:37], v[22:25]
	v_lshlrev_b64 v[26:27], 1, v[26:27]
	v_lshl_add_u64 v[40:41], s[54:55], 0, v[26:27]
	v_lshl_add_u64 v[26:27], s[74:75], 0, v[26:27]
	s_waitcnt vmcnt(1)
	v_lshlrev_b32_e32 v34, 16, v18
	v_and_b32_e32 v18, 0xffff0000, v18
	s_waitcnt vmcnt(0)
	s_nop 0
	v_add_f32_e32 v23, v23, v28
	v_lshlrev_b32_e32 v35, 16, v19
	v_and_b32_e32 v19, 0xffff0000, v19
	v_add_f32_e32 v25, v25, v28
	v_add_f32_e32 v22, v22, v28
	v_add_f32_e32 v24, v24, v28
	v_mul_f32_e32 v18, v23, v18
	v_mul_f32_e32 v19, v25, v19
	v_mul_f32_e32 v22, v22, v34
	v_mul_f32_e32 v23, v24, v35
	s_nop 1
	v_cvt_pk_bf16_f32 v18, v22, v18
	s_nop 1
	v_cvt_pk_bf16_f32 v19, v23, v19
	global_store_dwordx2 v[38:39], v[18:19], off
	global_load_dwordx2 v[18:19], v[40:41], off
	s_nop 0
	global_load_dword v28, v46, s[48:49] offset:256
	ds_read_b128 v[22:25], v47 offset:52224
	ds_read_b128 v[34:37], v47 offset:52288
	s_waitcnt lgkmcnt(1)
	v_mfma_f32_16x16x32_bf16 v[22:25], v[4:7], v[22:25], 0
	ds_read_b128 v[38:41], v47 offset:52352
	s_waitcnt lgkmcnt(1)
	v_mfma_f32_16x16x32_bf16 v[22:25], v[12:15], v[34:37], v[22:25]
	v_lshl_add_u64 v[34:35], v[16:17], 0, v[42:43]
	v_lshlrev_b64 v[42:43], 1, v[34:35]
	s_waitcnt vmcnt(1)
	v_lshlrev_b32_e32 v34, 16, v18
	s_waitcnt lgkmcnt(0)
	v_mfma_f32_16x16x32_bf16 v[22:25], v[8:11], v[38:41], v[22:25]
	v_and_b32_e32 v18, 0xffff0000, v18
	v_lshlrev_b32_e32 v35, 16, v19
	v_and_b32_e32 v19, 0xffff0000, v19
	v_lshl_add_u64 v[38:39], s[54:55], 0, v[42:43]
	v_lshl_add_u64 v[42:43], s[74:75], 0, v[42:43]
	s_waitcnt vmcnt(0)
	s_nop 1
	v_add_f32_e32 v23, v23, v28
	v_add_f32_e32 v25, v25, v28
	v_add_f32_e32 v22, v22, v28
	v_add_f32_e32 v24, v24, v28
	v_mul_f32_e32 v18, v23, v18
	v_mul_f32_e32 v19, v25, v19
	v_mul_f32_e32 v22, v22, v34
	v_mul_f32_e32 v23, v24, v35
	s_nop 1
	v_cvt_pk_bf16_f32 v18, v22, v18
	s_nop 1
	v_cvt_pk_bf16_f32 v19, v23, v19
	global_store_dwordx2 v[26:27], v[18:19], off
	global_load_dword v26, v46, s[48:49] offset:320
	ds_read_b128 v[22:25], v47 offset:56576
	ds_read_b128 v[34:37], v47 offset:56640
	global_load_dwordx2 v[18:19], v[38:39], off
	s_waitcnt lgkmcnt(1)
	v_mfma_f32_16x16x32_bf16 v[22:25], v[4:7], v[22:25], 0
	v_mov_b32_e32 v27, v21
	s_waitcnt vmcnt(0)
	v_lshlrev_b32_e32 v28, 16, v18
	s_waitcnt lgkmcnt(0)
	v_mfma_f32_16x16x32_bf16 v[22:25], v[12:15], v[34:37], v[22:25]
	ds_read_b128 v[34:37], v47 offset:56704
	v_and_b32_e32 v18, 0xffff0000, v18
	s_waitcnt lgkmcnt(0)
	v_mfma_f32_16x16x32_bf16 v[22:25], v[8:11], v[34:37], v[22:25]
	v_lshlrev_b32_e32 v34, 16, v19
	v_and_b32_e32 v19, 0xffff0000, v19
	s_nop 5
	v_add_f32_e32 v22, v22, v26
	v_add_f32_e32 v23, v23, v26
	v_add_f32_e32 v24, v24, v26
	v_add_f32_e32 v25, v25, v26
	v_or_b32_e32 v26, 0x18000, v20
	v_lshl_add_u64 v[26:27], v[16:17], 0, v[26:27]
	v_mul_f32_e32 v18, v23, v18
	v_mul_f32_e32 v19, v25, v19
	v_lshlrev_b64 v[26:27], 1, v[26:27]
	v_mul_f32_e32 v22, v22, v28
	v_mul_f32_e32 v23, v24, v34
	s_nop 1
	v_cvt_pk_bf16_f32 v18, v22, v18
	s_nop 1
	v_cvt_pk_bf16_f32 v19, v23, v19
	v_lshl_add_u64 v[44:45], s[54:55], 0, v[26:27]
	global_store_dwordx2 v[42:43], v[18:19], off
	global_load_dwordx2 v[18:19], v[44:45], off
	ds_read_b128 v[22:25], v47 offset:60928
	ds_read_b128 v[34:37], v47 offset:60992
	global_load_dword v28, v46, s[48:49] offset:384
	s_waitcnt lgkmcnt(1)
	v_mfma_f32_16x16x32_bf16 v[22:25], v[4:7], v[22:25], 0
	ds_read_b128 v[38:41], v47 offset:61056
	v_or_b32_e32 v20, 0x1c000, v20
	v_lshl_add_u64 v[16:17], v[16:17], 0, v[20:21]
	s_waitcnt lgkmcnt(1)
	v_mfma_f32_16x16x32_bf16 v[22:25], v[12:15], v[34:37], v[22:25]
	ds_read_b128 v[34:37], v47 offset:61120
	v_lshl_add_u64 v[26:27], s[74:75], 0, v[26:27]
	s_waitcnt lgkmcnt(1)
	v_mfma_f32_16x16x32_bf16 v[22:25], v[8:11], v[38:41], v[22:25]
	s_waitcnt lgkmcnt(0)
	v_mfma_f32_16x16x32_bf16 v[22:25], v[0:3], v[34:37], v[22:25]
	v_lshlrev_b64 v[36:37], 1, v[16:17]
	v_lshl_add_u64 v[38:39], s[54:55], 0, v[36:37]
	s_waitcnt vmcnt(1)
	v_lshlrev_b32_e32 v34, 16, v18
	v_and_b32_e32 v18, 0xffff0000, v18
	v_lshlrev_b32_e32 v35, 16, v19
	s_waitcnt vmcnt(0)
	s_nop 0
	v_add_f32_e32 v22, v22, v28
	v_add_f32_e32 v23, v23, v28
	v_add_f32_e32 v24, v24, v28
	v_and_b32_e32 v19, 0xffff0000, v19
	v_add_f32_e32 v25, v25, v28
	v_mul_f32_e32 v22, v22, v34
	v_mul_f32_e32 v18, v23, v18
	v_mul_f32_e32 v23, v24, v35
	v_mul_f32_e32 v19, v25, v19
	s_nop 1
	v_cvt_pk_bf16_f32 v34, v22, v18
	s_nop 1
	v_cvt_pk_bf16_f32 v35, v23, v19
	ds_read_b128 v[22:25], v47 offset:65280
	ds_read_b128 v[16:19], v47 offset:65344
	s_waitcnt lgkmcnt(1)
	v_mfma_f32_16x16x32_bf16 v[4:7], v[4:7], v[22:25], 0
	ds_read_b128 v[22:25], v47 offset:65408
	global_store_dwordx2 v[26:27], v[34:35], off
	s_waitcnt lgkmcnt(1)
	v_mfma_f32_16x16x32_bf16 v[4:7], v[12:15], v[16:19], v[4:7]
	ds_read_b128 v[12:15], v47 offset:65472
	global_load_dwordx2 v[16:17], v[38:39], off
	s_waitcnt lgkmcnt(1)
	v_mfma_f32_16x16x32_bf16 v[4:7], v[8:11], v[22:25], v[4:7]
	global_load_dword v10, v46, s[48:49] offset:448
	v_lshl_add_u64 v[8:9], s[74:75], 0, v[36:37]
	s_waitcnt lgkmcnt(0)
	v_mfma_f32_16x16x32_bf16 v[0:3], v[0:3], v[12:15], v[4:7]
	s_waitcnt vmcnt(1)
	s_nop 2
	v_lshlrev_b32_e32 v4, 16, v16
	v_and_b32_e32 v5, 0xffff0000, v16
	v_lshlrev_b32_e32 v6, 16, v17
	s_waitcnt vmcnt(0)
	v_add_f32_e32 v0, v0, v10
	v_add_f32_e32 v1, v1, v10
	v_add_f32_e32 v2, v2, v10
	v_and_b32_e32 v7, 0xffff0000, v17
	v_add_f32_e32 v3, v3, v10
	v_mul_f32_e32 v0, v0, v4
	v_mul_f32_e32 v1, v1, v5
	v_mul_f32_e32 v2, v2, v6
	v_mul_f32_e32 v3, v3, v7
	s_nop 1
	v_cvt_pk_bf16_f32 v0, v0, v1
	s_nop 1
	v_cvt_pk_bf16_f32 v1, v2, v3
	global_store_dwordx2 v[8:9], v[0:1], off
	s_barrier

.LBB0_1356:
	s_cmpk_gt_i32 s58, 0xff
	s_mov_b64 s[2:3], -1
	s_cbranch_scc0 .LBB0_1358
	s_lshl_b32 s2, s58, 4
	v_mov_b32_e32 v3, v183
	s_and_b32 s10, s2, 0x7fffff80
	s_addk_i32 s10, 0xf000
	v_ashrrev_i32_e32 v28, 4, v3
	v_add_u32_e32 v0, s10, v28
	v_ashrrev_i32_e32 v1, 31, v0
	s_and_b32 s11, s58, 7
	v_lshlrev_b64 v[120:121], 11, v[0:1]
	v_and_b32_e32 v122, 15, v3
	v_lshlrev_b32_e32 v122, 4, v122
	v_lshl_add_u32 v122, s11, 8, v122
	v_mov_b32_e32 v123, 0
	v_lshl_add_u64 v[120:121], v[120:121], 0, v[122:123]
	v_lshl_add_u64 v[124:125], s[34:35], 0, v[120:121]
	v_lshl_add_u64 v[126:127], s[30:31], 0, v[120:121]
	v_mov_b32_e32 v122, 0x10000
	global_load_dwordx4 v[116:119], v[124:125], off
	global_load_dwordx4 v[116:119], v[126:127], off
	v_lshl_add_u64 v[124:125], v[124:125], 0, v[122:123]
	v_lshl_add_u64 v[126:127], v[126:127], 0, v[122:123]
	global_load_dwordx4 v[116:119], v[124:125], off
	global_load_dwordx4 v[116:119], v[126:127], off
	v_lshl_add_u64 v[124:125], v[124:125], 0, v[122:123]
	v_lshl_add_u64 v[126:127], v[126:127], 0, v[122:123]
	global_load_dwordx4 v[116:119], v[124:125], off
	global_load_dwordx4 v[116:119], v[126:127], off
	v_lshl_add_u64 v[124:125], v[124:125], 0, v[122:123]
	v_lshl_add_u64 v[126:127], v[126:127], 0, v[122:123]
	global_load_dwordx4 v[116:119], v[124:125], off
	global_load_dwordx4 v[116:119], v[126:127], off
	v_lshlrev_b32_e32 v120, 4, v3
	v_lshl_add_u32 v120, s11, 16, v120
	v_mov_b32_e32 v121, 0
	v_lshl_add_u64 v[120:121], s[44:45], 0, v[120:121]
	v_mov_b32_e32 v122, 0x2000
	global_load_dwordx4 v[116:119], v[120:121], off
	v_lshl_add_u64 v[120:121], v[120:121], 0, v[122:123]
	global_load_dwordx4 v[116:119], v[120:121], off
	v_lshl_add_u64 v[120:121], v[120:121], 0, v[122:123]
	global_load_dwordx4 v[116:119], v[120:121], off
	v_lshl_add_u64 v[120:121], v[120:121], 0, v[122:123]
	global_load_dwordx4 v[116:119], v[120:121], off
	v_lshl_add_u64 v[120:121], v[120:121], 0, v[122:123]
	global_load_dwordx4 v[116:119], v[120:121], off
	v_lshl_add_u64 v[120:121], v[120:121], 0, v[122:123]
	global_load_dwordx4 v[116:119], v[120:121], off
	v_lshl_add_u64 v[120:121], v[120:121], 0, v[122:123]
	global_load_dwordx4 v[116:119], v[120:121], off
	v_lshl_add_u64 v[120:121], v[120:121], 0, v[122:123]
	global_load_dwordx4 v[116:119], v[120:121], off
	v_lshlrev_b64 v[4:5], 6, v[0:1]
	v_lshl_add_u64 v[4:5], s[0:1], 0, v[4:5]
	global_load_dwordx4 v[6:9], v[4:5], off offset:32
	global_load_dwordx4 v[10:13], v[4:5], off offset:16
	global_load_dwordx4 v[14:17], v[4:5], off offset:48
	global_load_dwordx4 v[22:25], v[4:5], off
	s_and_b32 s8, s58, 7
	v_lshlrev_b64 v[0:1], 11, v[0:1]
	s_lshl_b32 s48, s8, 8
	v_and_b32_e32 v4, 15, v3
	v_lshl_add_u64 v[0:1], s[34:35], 0, v[0:1]
	v_lshlrev_b32_e32 v20, 4, v4
	v_lshl_add_u64 v[0:1], v[0:1], 0, s[48:49]
	v_lshl_add_u64 v[0:1], v[0:1], 0, v[20:21]
	s_lshl_b32 s11, s8, 7
	s_lshl_b32 s2, s8, 9
	global_load_dwordx4 v[34:37], v[0:1], off
	s_add_u32 s2, s38, s2
	v_lshlrev_b32_e32 v0, 5, v4
	s_addc_u32 s3, s39, 0
	global_load_dwordx4 v[38:41], v0, s[2:3]
	global_load_dwordx4 v[42:45], v0, s[2:3] offset:16
	s_lshl_b32 s8, s8, 16
	v_lshlrev_b32_e32 v18, 7, v28
	s_add_u32 s8, s44, s8
	v_ashrrev_i32_e32 v19, 31, v18
	s_addc_u32 s9, s45, 0
	v_mov_b32_e32 v1, v21
	v_lshl_add_u64 v[18:19], v[18:19], 2, s[8:9]
	v_lshl_add_u64 v[18:19], v[18:19], 0, v[0:1]
	s_movk_i32 s12, 0x880
	s_waitcnt vmcnt(0)
	v_mov_b32_e32 v27, v6
	v_mov_b32_e32 v47, v8
	v_mov_b32_e32 v48, v10
	v_mov_b32_e32 v49, v14
	v_mov_b32_e32 v14, v11
	v_mov_b32_e32 v10, v12
	v_mov_b32_e32 v11, v16
	v_mov_b32_e32 v16, v13
	v_mov_b32_e32 v26, v22
	v_mov_b32_e32 v6, v23
	v_mov_b32_e32 v46, v24
	v_mov_b32_e32 v8, v25
	v_pk_add_f32 v[12:13], v[48:49], v[14:15]
	v_pk_add_f32 v[10:11], v[10:11], v[16:17]
	v_pk_add_f32 v[6:7], v[26:27], v[6:7]
	v_pk_add_f32 v[8:9], v[46:47], v[8:9]
	v_pk_add_f32 v[10:11], v[12:13], v[10:11]
	v_pk_add_f32 v[6:7], v[6:7], v[8:9]
	v_lshlrev_b32_e32 v12, 16, v34
	v_pk_add_f32 v[6:7], v[6:7], v[10:11]
	v_and_b32_e32 v13, 0xffff0000, v34
	v_add_f32_e32 v2, v6, v7
	v_fmamk_f32 v2, v2, 0x3a800000, v29
	v_mul_f32_e32 v5, 0x4b800000, v2
	v_cmp_gt_f32_e32 vcc, s25, v2
	v_lshlrev_b32_e32 v16, 16, v36
	v_and_b32_e32 v17, 0xffff0000, v36
	v_cndmask_b32_e32 v2, v2, v5, vcc
	v_rsq_f32_e32 v2, v2
	v_lshlrev_b32_e32 v14, 16, v35
	v_and_b32_e32 v15, 0xffff0000, v35
	v_lshlrev_b32_e32 v6, 16, v37
	v_mul_f32_e32 v5, 0x45800000, v2
	v_cndmask_b32_e32 v2, v2, v5, vcc
	v_and_b32_e32 v7, 0xffff0000, v37
	v_pk_mul_f32 v[8:9], v[2:3], v[12:13] op_sel_hi:[0,1]
	v_pk_mul_f32 v[12:13], v[2:3], v[16:17] op_sel_hi:[0,1]
	v_pk_mul_f32 v[10:11], v[2:3], v[14:15] op_sel_hi:[0,1]
	v_pk_mul_f32 v[6:7], v[2:3], v[6:7] op_sel_hi:[0,1]
	v_pk_mul_f32 v[12:13], v[42:43], v[12:13]
	v_pk_mul_f32 v[10:11], v[40:41], v[10:11]
	v_pk_mul_f32 v[8:9], v[38:39], v[8:9]
	v_pk_mul_f32 v[6:7], v[44:45], v[6:7]
	s_nop 1
	v_cvt_pk_bf16_f32 v36, v8, v9
	s_nop 1
	v_cvt_pk_bf16_f32 v37, v10, v11
	s_nop 1
	v_cvt_pk_bf16_f32 v13, v12, v13
	v_mad_u32_u24 v12, v4, s12, 16
	s_nop 1
	v_cvt_pk_bf16_f32 v38, v6, v7
	global_load_dwordx4 v[14:17], v[18:19], off
	global_load_dwordx4 v[22:25], v[18:19], off offset:16
	v_lshlrev_b32_e32 v7, 3, v4
	v_mov_b32_e32 v2, s49
	v_lshl_add_u32 v19, v28, 1, v12
	v_or_b32_e32 v11, 4, v7
	v_cmp_gt_i32_e32 vcc, v7, v28
	v_mov_b32_e32 v18, s49
	ds_write_b16 v19, v36
	ds_write_b16_d16_hi v19, v36 offset:272
	ds_write_b16 v19, v37 offset:544
	ds_write_b16_d16_hi v19, v37 offset:816
	ds_write_b16 v19, v13 offset:1088
	ds_write_b16_d16_hi v19, v13 offset:1360
	ds_write_b16 v19, v38 offset:1632
	ds_write_b16_d16_hi v19, v38 offset:1904
	v_or_b32_e32 v8, 5, v7
	v_add_u32_e32 v5, 0x200, v3
	v_or_b32_e32 v9, 6, v7
	v_ashrrev_i32_e32 v58, 4, v5
	v_or_b32_e32 v10, 7, v7
	v_or_b32_e32 v5, 2, v7
	v_add_u32_e32 v26, s10, v58
	v_or_b32_e32 v6, 3, v7
	v_ashrrev_i32_e32 v27, 31, v26
	v_lshlrev_b64 v[34:35], 6, v[26:27]
	v_lshl_add_u64 v[42:43], s[0:1], 0, v[34:35]
	s_movk_i32 s12, 0xf790
	s_waitcnt vmcnt(1)
	v_cndmask_b32_e32 v13, v16, v16, vcc
	v_cndmask_b32_e32 v19, v17, v17, vcc
	v_cndmask_b32_e32 v2, v14, v2, vcc
	v_cmp_gt_i32_e32 vcc, v11, v28
	s_waitcnt vmcnt(0)
	s_nop 0
	v_cndmask_b32_e32 v18, v22, v18, vcc
	v_cndmask_b32_e32 v22, v25, v25, vcc
	v_cndmask_b32_e32 v24, v24, v24, vcc
	v_cndmask_b32_e32 v23, v23, v23, vcc
	v_cmp_lt_i32_e32 vcc, v7, v28
	s_nop 1
	v_cndmask_b32_e32 v2, v2, v14, vcc
	v_cndmask_b32_e32 v14, v19, v17, vcc
	v_cndmask_b32_e32 v13, v13, v16, vcc
	v_cndmask_b32_e32 v15, 0, v15, vcc
	v_cmp_le_i32_e32 vcc, v8, v28
	s_nop 1
	v_cndmask_b32_e32 v16, 0, v23, vcc
	v_cmp_le_i32_e32 vcc, v9, v28
	s_nop 1
	v_cndmask_b32_e32 v17, 0, v24, vcc
	v_cmp_le_i32_e32 vcc, v10, v28
	s_nop 1
	v_cndmask_b32_e32 v19, 0, v22, vcc
	v_cmp_le_i32_e32 vcc, v5, v28
	s_nop 1
	v_cndmask_b32_e32 v13, 0, v13, vcc
	v_cmp_le_i32_e32 vcc, v6, v28
	s_nop 1
	v_cndmask_b32_e32 v22, 0, v14, vcc
	s_nop 1
	v_cvt_pk_bf16_f32 v14, v2, v15
	s_nop 1
	v_cvt_pk_bf16_f32 v15, v13, v22
	s_nop 1
	v_cvt_pk_bf16_f32 v16, v18, v16
	s_nop 1
	v_cvt_pk_bf16_f32 v17, v17, v19
	global_load_dwordx4 v[22:25], v[42:43], off
	global_load_dwordx4 v[34:37], v[42:43], off offset:32
	global_load_dwordx4 v[38:41], v[42:43], off offset:16
	s_nop 0
	global_load_dwordx4 v[42:45], v[42:43], off offset:48
	v_lshlrev_b64 v[18:19], 11, v[26:27]
	v_lshl_add_u64 v[18:19], s[34:35], 0, v[18:19]
	v_lshl_add_u64 v[18:19], v[18:19], 0, s[48:49]
	v_lshl_add_u64 v[18:19], v[18:19], 0, v[20:21]
	global_load_dwordx4 v[46:49], v[18:19], off
	global_load_dwordx4 v[50:53], v0, s[2:3]
	global_load_dwordx4 v[54:57], v0, s[2:3] offset:16
	v_mad_i32_i24 v2, v4, s12, v12
	v_mad_u64_u32 v[26:27], s[12:13], v28, s33, v[2:3]
	ds_write_b128 v26, v[14:17] offset:34816
	v_lshlrev_b32_e32 v18, 7, v58
	v_ashrrev_i32_e32 v19, 31, v18
	v_lshl_add_u64 v[18:19], v[18:19], 2, s[8:9]
	v_lshl_add_u64 v[18:19], v[18:19], 0, v[0:1]
	s_waitcnt vmcnt(6)
	v_mov_b32_e32 v14, v22
	s_waitcnt vmcnt(5)
	v_mov_b32_e32 v15, v34
	v_mov_b32_e32 v34, v23
	v_mov_b32_e32 v16, v24
	v_mov_b32_e32 v17, v36
	v_mov_b32_e32 v36, v25
	s_waitcnt vmcnt(4)
	v_mov_b32_e32 v22, v38
	s_waitcnt vmcnt(3)
	v_mov_b32_e32 v23, v42
	v_mov_b32_e32 v42, v39
	v_mov_b32_e32 v24, v40
	v_mov_b32_e32 v25, v44
	v_mov_b32_e32 v44, v41
	v_pk_add_f32 v[14:15], v[14:15], v[34:35]
	v_pk_add_f32 v[16:17], v[16:17], v[36:37]
	v_pk_add_f32 v[22:23], v[22:23], v[42:43]
	v_pk_add_f32 v[24:25], v[24:25], v[44:45]
	v_pk_add_f32 v[14:15], v[14:15], v[16:17]
	v_pk_add_f32 v[16:17], v[22:23], v[24:25]
	s_waitcnt vmcnt(2)
	v_lshlrev_b32_e32 v26, 16, v46
	v_pk_add_f32 v[14:15], v[14:15], v[16:17]
	v_and_b32_e32 v27, 0xffff0000, v46
	v_add_f32_e32 v13, v14, v15
	v_fmamk_f32 v13, v13, 0x3a800000, v29
	v_mul_f32_e32 v14, 0x4b800000, v13
	v_cmp_gt_f32_e32 vcc, s25, v13
	v_lshlrev_b32_e32 v38, 16, v47
	v_and_b32_e32 v39, 0xffff0000, v47
	v_cndmask_b32_e32 v13, v13, v14, vcc
	v_rsq_f32_e32 v13, v13
	v_lshlrev_b32_e32 v40, 16, v48
	v_and_b32_e32 v41, 0xffff0000, v48
	v_lshlrev_b32_e32 v14, 16, v49
	v_mul_f32_e32 v16, 0x45800000, v13
	v_and_b32_e32 v15, 0xffff0000, v49
	v_cndmask_b32_e32 v16, v13, v16, vcc
	v_pk_mul_f32 v[22:23], v[16:17], v[26:27] op_sel_hi:[0,1]
	v_pk_mul_f32 v[24:25], v[16:17], v[38:39] op_sel_hi:[0,1]
	v_pk_mul_f32 v[26:27], v[16:17], v[40:41] op_sel_hi:[0,1]
	v_pk_mul_f32 v[14:15], v[16:17], v[14:15] op_sel_hi:[0,1]
	s_waitcnt vmcnt(1)
	v_pk_mul_f32 v[16:17], v[52:53], v[24:25]
	v_pk_mul_f32 v[22:23], v[50:51], v[22:23]
	s_waitcnt vmcnt(0)
	v_pk_mul_f32 v[14:15], v[56:57], v[14:15]
	v_pk_mul_f32 v[24:25], v[54:55], v[26:27]
	s_nop 1
	v_cvt_pk_bf16_f32 v13, v22, v23
	s_nop 1
	v_cvt_pk_bf16_f32 v27, v16, v17
	v_cmp_gt_i32_e32 vcc, v7, v58
	s_nop 1
	v_cvt_pk_bf16_f32 v28, v24, v25
	s_nop 1
	v_cvt_pk_bf16_f32 v36, v14, v15
	global_load_dwordx4 v[14:17], v[18:19], off
	global_load_dwordx4 v[22:25], v[18:19], off offset:16
	v_add_u32_e32 v19, 0x400, v3
	v_mov_b32_e32 v18, s49
	v_ashrrev_i32_e32 v59, 4, v19
	v_lshl_add_u32 v19, v58, 1, v12
	v_mov_b32_e32 v26, s49
	ds_write_b16 v19, v13
	ds_write_b16_d16_hi v19, v13 offset:272
	ds_write_b16 v19, v27 offset:544
	ds_write_b16_d16_hi v19, v27 offset:816
	ds_write_b16 v19, v28 offset:1088
	ds_write_b16_d16_hi v19, v28 offset:1360
	ds_write_b16 v19, v36 offset:1632
	ds_write_b16_d16_hi v19, v36 offset:1904
	v_add_u32_e32 v46, s10, v59
	v_ashrrev_i32_e32 v47, 31, v46
	v_lshlrev_b64 v[34:35], 6, v[46:47]
	v_lshl_add_u64 v[42:43], s[0:1], 0, v[34:35]
	s_waitcnt vmcnt(1)
	v_cndmask_b32_e32 v13, v16, v16, vcc
	v_cndmask_b32_e32 v19, v17, v17, vcc
	v_cndmask_b32_e32 v18, v14, v18, vcc
	v_cmp_gt_i32_e32 vcc, v11, v58
	s_waitcnt vmcnt(0)
	s_nop 0
	v_cndmask_b32_e32 v22, v22, v26, vcc
	v_cndmask_b32_e32 v25, v25, v25, vcc
	v_cndmask_b32_e32 v24, v24, v24, vcc
	v_cndmask_b32_e32 v23, v23, v23, vcc
	v_cmp_lt_i32_e32 vcc, v7, v58
	v_mad_u64_u32 v[26:27], s[12:13], v58, s33, v[2:3]
	s_nop 0
	v_cndmask_b32_e32 v14, v18, v14, vcc
	v_cndmask_b32_e32 v17, v19, v17, vcc
	v_cndmask_b32_e32 v13, v13, v16, vcc
	v_cndmask_b32_e32 v15, 0, v15, vcc
	v_cmp_le_i32_e32 vcc, v8, v58
	s_nop 1
	v_cvt_pk_bf16_f32 v14, v14, v15
	s_nop 1
	v_cndmask_b32_e32 v16, 0, v23, vcc
	v_cmp_le_i32_e32 vcc, v9, v58
	s_nop 1
	v_cndmask_b32_e32 v18, 0, v24, vcc
	v_cmp_le_i32_e32 vcc, v10, v58
	s_nop 1
	v_cndmask_b32_e32 v19, 0, v25, vcc
	v_cmp_le_i32_e32 vcc, v5, v58
	s_nop 1
	v_cndmask_b32_e32 v13, 0, v13, vcc
	v_cmp_le_i32_e32 vcc, v6, v58
	s_nop 1
	v_cndmask_b32_e32 v17, 0, v17, vcc
	s_nop 1
	v_cvt_pk_bf16_f32 v15, v13, v17
	s_nop 1
	v_cvt_pk_bf16_f32 v16, v22, v16
	s_nop 1
	v_cvt_pk_bf16_f32 v17, v18, v19
	global_load_dwordx4 v[22:25], v[42:43], off
	global_load_dwordx4 v[34:37], v[42:43], off offset:32
	global_load_dwordx4 v[38:41], v[42:43], off offset:16
	s_nop 0
	global_load_dwordx4 v[42:45], v[42:43], off offset:48
	v_lshlrev_b64 v[18:19], 11, v[46:47]
	v_lshl_add_u64 v[18:19], s[34:35], 0, v[18:19]
	v_lshl_add_u64 v[18:19], v[18:19], 0, s[48:49]
	v_lshl_add_u64 v[18:19], v[18:19], 0, v[20:21]
	global_load_dwordx4 v[46:49], v[18:19], off
	global_load_dwordx4 v[50:53], v0, s[2:3]
	global_load_dwordx4 v[54:57], v0, s[2:3] offset:16
	ds_write_b128 v26, v[14:17] offset:34816
	v_lshlrev_b32_e32 v18, 7, v59
	v_ashrrev_i32_e32 v19, 31, v18
	v_lshl_add_u64 v[18:19], v[18:19], 2, s[8:9]
	v_lshl_add_u64 v[18:19], v[18:19], 0, v[0:1]
	s_waitcnt vmcnt(6)
	v_mov_b32_e32 v14, v22
	s_waitcnt vmcnt(5)
	v_mov_b32_e32 v15, v34
	v_mov_b32_e32 v34, v23
	v_mov_b32_e32 v16, v24
	v_mov_b32_e32 v17, v36
	v_mov_b32_e32 v36, v25
	s_waitcnt vmcnt(4)
	v_mov_b32_e32 v22, v38
	s_waitcnt vmcnt(3)
	v_mov_b32_e32 v23, v42
	v_mov_b32_e32 v42, v39
	v_mov_b32_e32 v24, v40
	v_mov_b32_e32 v25, v44
	v_mov_b32_e32 v44, v41
	v_pk_add_f32 v[14:15], v[14:15], v[34:35]
	v_pk_add_f32 v[16:17], v[16:17], v[36:37]
	v_pk_add_f32 v[22:23], v[22:23], v[42:43]
	v_pk_add_f32 v[24:25], v[24:25], v[44:45]
	v_pk_add_f32 v[14:15], v[14:15], v[16:17]
	v_pk_add_f32 v[16:17], v[22:23], v[24:25]
	s_waitcnt vmcnt(2)
	v_lshlrev_b32_e32 v26, 16, v46
	v_pk_add_f32 v[14:15], v[14:15], v[16:17]
	v_and_b32_e32 v27, 0xffff0000, v46
	v_add_f32_e32 v13, v14, v15
	v_fmamk_f32 v13, v13, 0x3a800000, v29
	v_mul_f32_e32 v14, 0x4b800000, v13
	v_cmp_gt_f32_e32 vcc, s25, v13
	v_lshlrev_b32_e32 v38, 16, v47
	v_and_b32_e32 v39, 0xffff0000, v47
	v_cndmask_b32_e32 v13, v13, v14, vcc
	v_rsq_f32_e32 v13, v13
	v_lshlrev_b32_e32 v40, 16, v48
	v_and_b32_e32 v41, 0xffff0000, v48
	v_lshlrev_b32_e32 v14, 16, v49
	v_mul_f32_e32 v16, 0x45800000, v13
	v_and_b32_e32 v15, 0xffff0000, v49
	v_cndmask_b32_e32 v16, v13, v16, vcc
	v_pk_mul_f32 v[22:23], v[16:17], v[26:27] op_sel_hi:[0,1]
	v_pk_mul_f32 v[24:25], v[16:17], v[38:39] op_sel_hi:[0,1]
	v_pk_mul_f32 v[26:27], v[16:17], v[40:41] op_sel_hi:[0,1]
	v_pk_mul_f32 v[14:15], v[16:17], v[14:15] op_sel_hi:[0,1]
	s_waitcnt vmcnt(1)
	v_pk_mul_f32 v[16:17], v[52:53], v[24:25]
	v_pk_mul_f32 v[22:23], v[50:51], v[22:23]
	s_waitcnt vmcnt(0)
	v_pk_mul_f32 v[14:15], v[56:57], v[14:15]
	v_pk_mul_f32 v[24:25], v[54:55], v[26:27]
	s_nop 1
	v_cvt_pk_bf16_f32 v13, v22, v23
	s_nop 1
	v_cvt_pk_bf16_f32 v27, v16, v17
	v_cmp_gt_i32_e32 vcc, v7, v59
	s_nop 1
	v_cvt_pk_bf16_f32 v28, v24, v25
	s_nop 1
	v_cvt_pk_bf16_f32 v36, v14, v15
	global_load_dwordx4 v[14:17], v[18:19], off
	global_load_dwordx4 v[22:25], v[18:19], off offset:16
	v_add_u32_e32 v19, 0x600, v3
	v_mov_b32_e32 v18, s49
	v_ashrrev_i32_e32 v58, 4, v19
	v_lshl_add_u32 v19, v59, 1, v12
	v_mov_b32_e32 v26, s49
	ds_write_b16 v19, v13
	ds_write_b16_d16_hi v19, v13 offset:272
	ds_write_b16 v19, v27 offset:544
	ds_write_b16_d16_hi v19, v27 offset:816
	ds_write_b16 v19, v28 offset:1088
	ds_write_b16_d16_hi v19, v28 offset:1360
	ds_write_b16 v19, v36 offset:1632
	ds_write_b16_d16_hi v19, v36 offset:1904
	v_add_u32_e32 v46, s10, v58
	v_ashrrev_i32_e32 v47, 31, v46
	v_lshlrev_b64 v[34:35], 6, v[46:47]
	v_lshl_add_u64 v[42:43], s[0:1], 0, v[34:35]
	s_waitcnt vmcnt(1)
	v_cndmask_b32_e32 v13, v16, v16, vcc
	v_cndmask_b32_e32 v19, v17, v17, vcc
	v_cndmask_b32_e32 v18, v14, v18, vcc
	v_cmp_gt_i32_e32 vcc, v11, v59
	s_waitcnt vmcnt(0)
	s_nop 0
	v_cndmask_b32_e32 v22, v22, v26, vcc
	v_cndmask_b32_e32 v25, v25, v25, vcc
	v_cndmask_b32_e32 v24, v24, v24, vcc
	v_cndmask_b32_e32 v23, v23, v23, vcc
	v_cmp_lt_i32_e32 vcc, v7, v59
	s_nop 1
	v_cndmask_b32_e32 v14, v18, v14, vcc
	v_cndmask_b32_e32 v17, v19, v17, vcc
	v_cndmask_b32_e32 v13, v13, v16, vcc
	v_cndmask_b32_e32 v15, 0, v15, vcc
	v_cmp_le_i32_e32 vcc, v8, v59
	s_nop 1
	v_cvt_pk_bf16_f32 v14, v14, v15
	s_nop 1
	v_cndmask_b32_e32 v16, 0, v23, vcc
	v_cmp_le_i32_e32 vcc, v9, v59
	s_nop 1
	v_cndmask_b32_e32 v18, 0, v24, vcc
	v_cmp_le_i32_e32 vcc, v10, v59
	s_nop 1
	v_cndmask_b32_e32 v19, 0, v25, vcc
	v_cmp_le_i32_e32 vcc, v5, v59
	s_nop 1
	v_cndmask_b32_e32 v13, 0, v13, vcc
	v_cmp_le_i32_e32 vcc, v6, v59
	s_nop 1
	v_cndmask_b32_e32 v17, 0, v17, vcc
	s_nop 1
	v_cvt_pk_bf16_f32 v15, v13, v17
	s_nop 1
	v_cvt_pk_bf16_f32 v16, v22, v16
	s_nop 1
	v_cvt_pk_bf16_f32 v17, v18, v19
	global_load_dwordx4 v[22:25], v[42:43], off
	global_load_dwordx4 v[34:37], v[42:43], off offset:32
	global_load_dwordx4 v[38:41], v[42:43], off offset:16
	s_nop 0
	global_load_dwordx4 v[42:45], v[42:43], off offset:48
	v_lshlrev_b64 v[18:19], 11, v[46:47]
	v_lshl_add_u64 v[18:19], s[34:35], 0, v[18:19]
	v_lshl_add_u64 v[18:19], v[18:19], 0, s[48:49]
	v_lshl_add_u64 v[18:19], v[18:19], 0, v[20:21]
	global_load_dwordx4 v[46:49], v[18:19], off
	global_load_dwordx4 v[50:53], v0, s[2:3]
	global_load_dwordx4 v[54:57], v0, s[2:3] offset:16
	v_lshlrev_b32_e32 v18, 7, v58
	v_ashrrev_i32_e32 v19, 31, v18
	v_mad_u64_u32 v[26:27], s[2:3], v59, s33, v[2:3]
	v_lshl_add_u64 v[18:19], v[18:19], 2, s[8:9]
	v_lshl_add_u64 v[0:1], v[18:19], 0, v[0:1]
	ds_write_b128 v26, v[14:17] offset:34816
	s_waitcnt vmcnt(6)
	v_mov_b32_e32 v14, v22
	s_waitcnt vmcnt(5)
	v_mov_b32_e32 v15, v34
	v_mov_b32_e32 v34, v23
	v_mov_b32_e32 v16, v24
	v_mov_b32_e32 v17, v36
	v_mov_b32_e32 v36, v25
	s_waitcnt vmcnt(4)
	v_mov_b32_e32 v18, v38
	s_waitcnt vmcnt(3)
	v_mov_b32_e32 v19, v42
	v_mov_b32_e32 v42, v39
	v_mov_b32_e32 v22, v40
	v_mov_b32_e32 v23, v44
	v_mov_b32_e32 v44, v41
	v_pk_add_f32 v[14:15], v[14:15], v[34:35]
	v_pk_add_f32 v[16:17], v[16:17], v[36:37]
	v_pk_add_f32 v[18:19], v[18:19], v[42:43]
	v_pk_add_f32 v[22:23], v[22:23], v[44:45]
	v_pk_add_f32 v[14:15], v[14:15], v[16:17]
	v_pk_add_f32 v[16:17], v[18:19], v[22:23]
	s_waitcnt vmcnt(2)
	v_lshlrev_b32_e32 v24, 16, v46
	v_pk_add_f32 v[14:15], v[14:15], v[16:17]
	v_and_b32_e32 v25, 0xffff0000, v46
	v_add_f32_e32 v13, v14, v15
	v_fmamk_f32 v13, v13, 0x3a800000, v29
	v_mul_f32_e32 v14, 0x4b800000, v13
	v_cmp_gt_f32_e32 vcc, s25, v13
	v_lshlrev_b32_e32 v26, 16, v47
	v_and_b32_e32 v27, 0xffff0000, v47
	v_cndmask_b32_e32 v13, v13, v14, vcc
	v_rsq_f32_e32 v13, v13
	v_lshlrev_b32_e32 v38, 16, v48
	v_and_b32_e32 v39, 0xffff0000, v48
	v_lshlrev_b32_e32 v14, 16, v49
	v_mul_f32_e32 v16, 0x45800000, v13
	v_and_b32_e32 v15, 0xffff0000, v49
	v_cndmask_b32_e32 v16, v13, v16, vcc
	v_pk_mul_f32 v[18:19], v[16:17], v[24:25] op_sel_hi:[0,1]
	v_pk_mul_f32 v[22:23], v[16:17], v[26:27] op_sel_hi:[0,1]
	v_pk_mul_f32 v[24:25], v[16:17], v[38:39] op_sel_hi:[0,1]
	v_pk_mul_f32 v[14:15], v[16:17], v[14:15] op_sel_hi:[0,1]
	s_waitcnt vmcnt(1)
	v_pk_mul_f32 v[16:17], v[52:53], v[22:23]
	s_waitcnt vmcnt(0)
	v_pk_mul_f32 v[14:15], v[56:57], v[14:15]
	v_pk_mul_f32 v[22:23], v[54:55], v[24:25]
	v_pk_mul_f32 v[18:19], v[50:51], v[18:19]
	v_ashrrev_i32_e32 v41, 2, v3
	s_nop 1
	v_cvt_pk_bf16_f32 v28, v18, v19
	s_nop 1
	v_cvt_pk_bf16_f32 v38, v16, v17
	s_nop 1
	v_cvt_pk_bf16_f32 v39, v22, v23
	s_nop 1
	v_cvt_pk_bf16_f32 v15, v14, v15
	global_load_dwordx4 v[22:25], v[0:1], off
	global_load_dwordx4 v[34:37], v[0:1], off offset:16
	v_mov_b32_e32 v0, s49
	v_bfe_u32 v40, v3, 4, 2
	v_and_b32_e32 v1, -16, v41
	v_or_b32_e32 v13, s11, v4
	v_cmp_gt_i32_e32 vcc, v7, v58
	v_mov_b32_e32 v14, s49
	v_lshl_add_u32 v42, v58, 1, v12
	v_ashrrev_i32_e32 v17, 31, v1
	v_lshl_or_b32 v16, v40, 2, v1
	v_lshlrev_b32_e32 v46, 2, v13
	v_mad_u64_u32 v[12:13], s[2:3], v58, s33, v[2:3]
	ds_write_b16 v42, v28
	ds_write_b16_d16_hi v42, v28 offset:272
	ds_write_b16 v42, v38 offset:544
	ds_write_b16_d16_hi v42, v38 offset:816
	ds_write_b16 v42, v39 offset:1088
	ds_write_b16_d16_hi v42, v39 offset:1360
	ds_write_b16 v42, v15 offset:1632
	ds_write_b16_d16_hi v42, v15 offset:1904
	v_or_b32_e32 v18, s10, v4
	v_lshl_or_b32 v20, v18, 10, s11
	v_lshl_add_u64 v[18:19], v[16:17], 0, v[20:21]
	v_lshlrev_b64 v[18:19], 1, v[18:19]
	v_lshl_add_u64 v[26:27], s[30:31], 0, v[18:19]
	v_lshl_add_u64 v[18:19], s[36:37], 0, v[18:19]
	v_mov_b32_e32 v43, v21
	v_or_b32_e32 v42, 0x14000, v20
	s_waitcnt vmcnt(1)
	v_cndmask_b32_e32 v1, v24, v24, vcc
	v_cndmask_b32_e32 v2, v25, v25, vcc
	v_cndmask_b32_e32 v0, v22, v0, vcc
	v_cmp_gt_i32_e32 vcc, v11, v58
	s_waitcnt vmcnt(0)
	s_nop 0
	v_cndmask_b32_e32 v11, v34, v14, vcc
	v_cndmask_b32_e32 v13, v37, v37, vcc
	v_cndmask_b32_e32 v14, v36, v36, vcc
	v_cndmask_b32_e32 v15, v35, v35, vcc
	v_cmp_lt_i32_e32 vcc, v7, v58
	s_nop 1
	v_cndmask_b32_e32 v0, v0, v22, vcc
	v_cndmask_b32_e32 v2, v2, v25, vcc
	v_cndmask_b32_e32 v1, v1, v24, vcc
	v_cndmask_b32_e32 v7, 0, v23, vcc
	v_cmp_le_i32_e32 vcc, v8, v58
	s_nop 1
	v_cndmask_b32_e32 v8, 0, v15, vcc
	v_cmp_le_i32_e32 vcc, v9, v58
	s_nop 1
	v_cndmask_b32_e32 v9, 0, v14, vcc
	v_cmp_le_i32_e32 vcc, v10, v58
	s_nop 1
	v_cndmask_b32_e32 v10, 0, v13, vcc
	v_cmp_le_i32_e32 vcc, v5, v58
	s_nop 1
	v_cndmask_b32_e32 v1, 0, v1, vcc
	v_cmp_le_i32_e32 vcc, v6, v58
	s_nop 1
	v_cvt_pk_bf16_f32 v6, v0, v7
	v_lshl_add_u32 v0, v40, 4, 16
	v_mad_u32_u24 v47, v4, s33, v0
	v_cndmask_b32_e32 v2, 0, v2, vcc
	s_nop 1
	v_cvt_pk_bf16_f32 v7, v1, v2
	s_nop 1
	v_cvt_pk_bf16_f32 v8, v11, v8
	s_nop 1
	v_cvt_pk_bf16_f32 v9, v9, v10
	ds_write_b128 v12, v[6:9] offset:34816
	s_waitcnt lgkmcnt(0)
	s_barrier
	global_load_dwordx2 v[26:27], v[26:27], off
	s_nop 0
	global_load_dword v28, v46, s[46:47]
	v_mov_b32_e32 v1, v21
	v_bfi_b32 v2, -16, v41, v3
	v_mad_u64_u32 v[2:3], s[2:3], v2, s33, v[0:1]
	ds_read_b128 v[4:7], v2
	ds_read_b128 v[22:25], v47 offset:34816
	s_waitcnt lgkmcnt(0)
	v_mfma_f32_16x16x32_bf16 v[22:25], v[4:7], v[22:25], 0
	v_or_b32_e32 v0, 0x4000, v20
	v_lshl_add_u64 v[0:1], v[16:17], 0, v[0:1]
	v_lshlrev_b64 v[34:35], 1, v[0:1]
	v_lshl_add_u64 v[36:37], s[30:31], 0, v[34:35]
	ds_read_b128 v[12:15], v2 offset:64
	ds_read_b128 v[8:11], v2 offset:128
	ds_read_b128 v[0:3], v2 offset:192
	v_lshl_add_u64 v[34:35], s[36:37], 0, v[34:35]
	s_mov_b64 s[2:3], 0
	s_waitcnt vmcnt(1)
	v_lshlrev_b32_e32 v38, 16, v26
	s_waitcnt vmcnt(0)
	v_add_f32_e32 v22, v22, v28
	v_and_b32_e32 v26, 0xffff0000, v26
	v_add_f32_e32 v23, v23, v28
	v_lshlrev_b32_e32 v39, 16, v27
	v_add_f32_e32 v24, v24, v28
	v_and_b32_e32 v27, 0xffff0000, v27
	v_add_f32_e32 v25, v25, v28
	v_mul_f32_e32 v22, v22, v38
	v_mul_f32_e32 v23, v23, v26
	v_mul_f32_e32 v24, v24, v39
	v_mul_f32_e32 v25, v25, v27
	s_nop 1
	v_cvt_pk_bf16_f32 v22, v22, v23
	s_nop 1
	v_cvt_pk_bf16_f32 v23, v24, v25
	global_store_dwordx2 v[18:19], v[22:23], off
	global_load_dwordx2 v[18:19], v[36:37], off
	s_nop 0
	global_load_dword v28, v46, s[46:47] offset:64
	ds_read_b128 v[22:25], v47 offset:39168
	s_waitcnt lgkmcnt(0)
	v_mfma_f32_16x16x32_bf16 v[22:25], v[4:7], v[22:25], 0
	v_mov_b32_e32 v27, v21
	v_or_b32_e32 v26, 0x8000, v20
	v_lshl_add_u64 v[26:27], v[16:17], 0, v[26:27]
	v_lshlrev_b64 v[26:27], 1, v[26:27]
	v_lshl_add_u64 v[36:37], s[30:31], 0, v[26:27]
	v_lshl_add_u64 v[26:27], s[36:37], 0, v[26:27]
	s_waitcnt vmcnt(1)
	v_lshlrev_b32_e32 v38, 16, v18
	v_and_b32_e32 v18, 0xffff0000, v18
	s_waitcnt vmcnt(0)
	v_add_f32_e32 v23, v23, v28
	v_lshlrev_b32_e32 v39, 16, v19
	v_and_b32_e32 v19, 0xffff0000, v19
	v_add_f32_e32 v25, v25, v28
	v_add_f32_e32 v22, v22, v28
	v_add_f32_e32 v24, v24, v28
	v_mul_f32_e32 v18, v23, v18
	v_mul_f32_e32 v19, v25, v19
	v_mul_f32_e32 v22, v22, v38
	v_mul_f32_e32 v23, v24, v39
	s_nop 1
	v_cvt_pk_bf16_f32 v18, v22, v18
	s_nop 1
	v_cvt_pk_bf16_f32 v19, v23, v19
	global_store_dwordx2 v[34:35], v[18:19], off
	global_load_dwordx2 v[18:19], v[36:37], off
	s_nop 0
	global_load_dword v28, v46, s[46:47] offset:128
	ds_read_b128 v[22:25], v47 offset:43520
	v_mov_b32_e32 v35, v21
	v_or_b32_e32 v34, 0xc000, v20
	v_lshl_add_u64 v[38:39], v[16:17], 0, v[34:35]
	ds_read_b128 v[34:37], v47 offset:43584
	s_waitcnt lgkmcnt(1)
	v_mfma_f32_16x16x32_bf16 v[22:25], v[4:7], v[22:25], 0
	v_lshlrev_b64 v[38:39], 1, v[38:39]
	v_lshl_add_u64 v[40:41], s[30:31], 0, v[38:39]
	v_lshl_add_u64 v[38:39], s[36:37], 0, v[38:39]
	s_waitcnt lgkmcnt(0)
	v_mfma_f32_16x16x32_bf16 v[22:25], v[12:15], v[34:37], v[22:25]
	s_waitcnt vmcnt(1)
	v_lshlrev_b32_e32 v34, 16, v18
	v_and_b32_e32 v18, 0xffff0000, v18
	s_waitcnt vmcnt(0)
	s_nop 3
	v_add_f32_e32 v23, v23, v28
	v_lshlrev_b32_e32 v35, 16, v19
	v_and_b32_e32 v19, 0xffff0000, v19
	v_add_f32_e32 v25, v25, v28
	v_add_f32_e32 v22, v22, v28
	v_add_f32_e32 v24, v24, v28
	v_mul_f32_e32 v18, v23, v18
	v_mul_f32_e32 v19, v25, v19
	v_mul_f32_e32 v22, v22, v34
	v_mul_f32_e32 v23, v24, v35
	s_nop 1
	v_cvt_pk_bf16_f32 v18, v22, v18
	s_nop 1
	v_cvt_pk_bf16_f32 v19, v23, v19
	global_store_dwordx2 v[26:27], v[18:19], off
	global_load_dwordx2 v[18:19], v[40:41], off
	s_nop 0
	global_load_dword v28, v46, s[46:47] offset:192
	ds_read_b128 v[22:25], v47 offset:47872
	ds_read_b128 v[34:37], v47 offset:47936
	s_waitcnt lgkmcnt(1)
	v_mfma_f32_16x16x32_bf16 v[22:25], v[4:7], v[22:25], 0
	v_mov_b32_e32 v27, v21
	v_or_b32_e32 v26, 0x10000, v20
	v_lshl_add_u64 v[26:27], v[16:17], 0, v[26:27]
	s_waitcnt lgkmcnt(0)
	v_mfma_f32_16x16x32_bf16 v[22:25], v[12:15], v[34:37], v[22:25]
	v_lshlrev_b64 v[26:27], 1, v[26:27]
	v_lshl_add_u64 v[40:41], s[30:31], 0, v[26:27]
	v_lshl_add_u64 v[26:27], s[36:37], 0, v[26:27]
	s_waitcnt vmcnt(1)
	v_lshlrev_b32_e32 v34, 16, v18
	v_and_b32_e32 v18, 0xffff0000, v18
	s_waitcnt vmcnt(0)
	s_nop 0
	v_add_f32_e32 v23, v23, v28
	v_lshlrev_b32_e32 v35, 16, v19
	v_and_b32_e32 v19, 0xffff0000, v19
	v_add_f32_e32 v25, v25, v28
	v_add_f32_e32 v22, v22, v28
	v_add_f32_e32 v24, v24, v28
	v_mul_f32_e32 v18, v23, v18
	v_mul_f32_e32 v19, v25, v19
	v_mul_f32_e32 v22, v22, v34
	v_mul_f32_e32 v23, v24, v35
	s_nop 1
	v_cvt_pk_bf16_f32 v18, v22, v18
	s_nop 1
	v_cvt_pk_bf16_f32 v19, v23, v19
	global_store_dwordx2 v[38:39], v[18:19], off
	global_load_dwordx2 v[18:19], v[40:41], off
	s_nop 0
	global_load_dword v28, v46, s[46:47] offset:256
	ds_read_b128 v[22:25], v47 offset:52224
	ds_read_b128 v[34:37], v47 offset:52288
	s_waitcnt lgkmcnt(1)
	v_mfma_f32_16x16x32_bf16 v[22:25], v[4:7], v[22:25], 0
	ds_read_b128 v[38:41], v47 offset:52352
	s_waitcnt lgkmcnt(1)
	v_mfma_f32_16x16x32_bf16 v[22:25], v[12:15], v[34:37], v[22:25]
	v_lshl_add_u64 v[34:35], v[16:17], 0, v[42:43]
	v_lshlrev_b64 v[42:43], 1, v[34:35]
	s_waitcnt vmcnt(1)
	v_lshlrev_b32_e32 v34, 16, v18
	s_waitcnt lgkmcnt(0)
	v_mfma_f32_16x16x32_bf16 v[22:25], v[8:11], v[38:41], v[22:25]
	v_and_b32_e32 v18, 0xffff0000, v18
	v_lshlrev_b32_e32 v35, 16, v19
	v_and_b32_e32 v19, 0xffff0000, v19
	v_lshl_add_u64 v[38:39], s[30:31], 0, v[42:43]
	v_lshl_add_u64 v[42:43], s[36:37], 0, v[42:43]
	s_waitcnt vmcnt(0)
	s_nop 1
	v_add_f32_e32 v23, v23, v28
	v_add_f32_e32 v25, v25, v28
	v_add_f32_e32 v22, v22, v28
	v_add_f32_e32 v24, v24, v28
	v_mul_f32_e32 v18, v23, v18
	v_mul_f32_e32 v19, v25, v19
	v_mul_f32_e32 v22, v22, v34
	v_mul_f32_e32 v23, v24, v35
	s_nop 1
	v_cvt_pk_bf16_f32 v18, v22, v18
	s_nop 1
	v_cvt_pk_bf16_f32 v19, v23, v19
	global_store_dwordx2 v[26:27], v[18:19], off
	global_load_dword v26, v46, s[46:47] offset:320
	ds_read_b128 v[22:25], v47 offset:56576
	ds_read_b128 v[34:37], v47 offset:56640
	global_load_dwordx2 v[18:19], v[38:39], off
	s_waitcnt lgkmcnt(1)
	v_mfma_f32_16x16x32_bf16 v[22:25], v[4:7], v[22:25], 0
	v_mov_b32_e32 v27, v21
	s_waitcnt vmcnt(0)
	v_lshlrev_b32_e32 v28, 16, v18
	s_waitcnt lgkmcnt(0)
	v_mfma_f32_16x16x32_bf16 v[22:25], v[12:15], v[34:37], v[22:25]
	ds_read_b128 v[34:37], v47 offset:56704
	v_and_b32_e32 v18, 0xffff0000, v18
	s_waitcnt lgkmcnt(0)
	v_mfma_f32_16x16x32_bf16 v[22:25], v[8:11], v[34:37], v[22:25]
	v_lshlrev_b32_e32 v34, 16, v19
	v_and_b32_e32 v19, 0xffff0000, v19
	s_nop 5
	v_add_f32_e32 v22, v22, v26
	v_add_f32_e32 v23, v23, v26
	v_add_f32_e32 v24, v24, v26
	v_add_f32_e32 v25, v25, v26
	v_or_b32_e32 v26, 0x18000, v20
	v_lshl_add_u64 v[26:27], v[16:17], 0, v[26:27]
	v_mul_f32_e32 v18, v23, v18
	v_mul_f32_e32 v19, v25, v19
	v_lshlrev_b64 v[26:27], 1, v[26:27]
	v_mul_f32_e32 v22, v22, v28
	v_mul_f32_e32 v23, v24, v34
	s_nop 1
	v_cvt_pk_bf16_f32 v18, v22, v18
	s_nop 1
	v_cvt_pk_bf16_f32 v19, v23, v19
	v_lshl_add_u64 v[44:45], s[30:31], 0, v[26:27]
	global_store_dwordx2 v[42:43], v[18:19], off
	global_load_dwordx2 v[18:19], v[44:45], off
	ds_read_b128 v[22:25], v47 offset:60928
	ds_read_b128 v[34:37], v47 offset:60992
	global_load_dword v28, v46, s[46:47] offset:384
	s_waitcnt lgkmcnt(1)
	v_mfma_f32_16x16x32_bf16 v[22:25], v[4:7], v[22:25], 0
	ds_read_b128 v[38:41], v47 offset:61056
	v_or_b32_e32 v20, 0x1c000, v20
	v_lshl_add_u64 v[16:17], v[16:17], 0, v[20:21]
	s_waitcnt lgkmcnt(1)
	v_mfma_f32_16x16x32_bf16 v[22:25], v[12:15], v[34:37], v[22:25]
	ds_read_b128 v[34:37], v47 offset:61120
	v_lshl_add_u64 v[26:27], s[36:37], 0, v[26:27]
	s_waitcnt lgkmcnt(1)
	v_mfma_f32_16x16x32_bf16 v[22:25], v[8:11], v[38:41], v[22:25]
	s_waitcnt lgkmcnt(0)
	v_mfma_f32_16x16x32_bf16 v[22:25], v[0:3], v[34:37], v[22:25]
	v_lshlrev_b64 v[36:37], 1, v[16:17]
	v_lshl_add_u64 v[38:39], s[30:31], 0, v[36:37]
	s_waitcnt vmcnt(1)
	v_lshlrev_b32_e32 v34, 16, v18
	v_and_b32_e32 v18, 0xffff0000, v18
	v_lshlrev_b32_e32 v35, 16, v19
	s_waitcnt vmcnt(0)
	s_nop 0
	v_add_f32_e32 v22, v22, v28
	v_add_f32_e32 v23, v23, v28
	v_add_f32_e32 v24, v24, v28
	v_and_b32_e32 v19, 0xffff0000, v19
	v_add_f32_e32 v25, v25, v28
	v_mul_f32_e32 v22, v22, v34
	v_mul_f32_e32 v18, v23, v18
	v_mul_f32_e32 v23, v24, v35
	v_mul_f32_e32 v19, v25, v19
	s_nop 1
	v_cvt_pk_bf16_f32 v34, v22, v18
	s_nop 1
	v_cvt_pk_bf16_f32 v35, v23, v19
	ds_read_b128 v[22:25], v47 offset:65280
	ds_read_b128 v[16:19], v47 offset:65344
	s_waitcnt lgkmcnt(1)
	v_mfma_f32_16x16x32_bf16 v[4:7], v[4:7], v[22:25], 0
	ds_read_b128 v[22:25], v47 offset:65408
	global_store_dwordx2 v[26:27], v[34:35], off
	s_waitcnt lgkmcnt(1)
	v_mfma_f32_16x16x32_bf16 v[4:7], v[12:15], v[16:19], v[4:7]
	ds_read_b128 v[12:15], v47 offset:65472
	global_load_dwordx2 v[16:17], v[38:39], off
	s_waitcnt lgkmcnt(1)
	v_mfma_f32_16x16x32_bf16 v[4:7], v[8:11], v[22:25], v[4:7]
	global_load_dword v10, v46, s[46:47] offset:448
	v_lshl_add_u64 v[8:9], s[36:37], 0, v[36:37]
	s_waitcnt lgkmcnt(0)
	v_mfma_f32_16x16x32_bf16 v[0:3], v[0:3], v[12:15], v[4:7]
	s_waitcnt vmcnt(1)
	s_nop 2
	v_lshlrev_b32_e32 v4, 16, v16
	v_and_b32_e32 v5, 0xffff0000, v16
	v_lshlrev_b32_e32 v6, 16, v17
	s_waitcnt vmcnt(0)
	v_add_f32_e32 v0, v0, v10
	v_add_f32_e32 v1, v1, v10
	v_add_f32_e32 v2, v2, v10
	v_and_b32_e32 v7, 0xffff0000, v17
	v_add_f32_e32 v3, v3, v10
	v_mul_f32_e32 v0, v0, v4
	v_mul_f32_e32 v1, v1, v5
	v_mul_f32_e32 v2, v2, v6
	v_mul_f32_e32 v3, v3, v7
	s_nop 1
	v_cvt_pk_bf16_f32 v0, v0, v1
	s_nop 1
	v_cvt_pk_bf16_f32 v1, v2, v3
	global_store_dwordx2 v[8:9], v[0:1], off
	s_barrier
